# wave-sum reductions in P0/P4/P8 norm phases: ds_bpermute xor stages 1,2,4,8 replaced by DPP moves and xor 32 by v_permlane32_swap (xor 16 stays ds_bpermute)
# baseline (speedup 1.0000x reference)
.LBB0_388:
	v_add_u32_e32 v18, -1, v86
	v_ashrrev_i32_e32 v19, 31, v18
	v_lshlrev_b64 v[2:3], 6, v[18:19]
	v_lshl_add_u64 v[14:15], s[66:67], 0, v[2:3]
	global_load_dwordx4 v[2:5], v[14:15], off offset:32
	global_load_dwordx4 v[6:9], v[14:15], off offset:48
	global_load_dwordx4 v[10:13], v[14:15], off
	s_nop 0
	global_load_dwordx4 v[14:17], v[14:15], off offset:16
	v_lshlrev_b64 v[20:21], 12, v[18:19]
	v_lshlrev_b64 v[94:95], 11, v[18:19]
	v_ashrrev_i32_e32 v87, 31, v86
	v_lshlrev_b64 v[18:19], 12, v[86:87]
	v_lshlrev_b64 v[92:93], 11, v[86:87]
	v_add_u32_e32 v192, s2, v192
	s_waitcnt vmcnt(0)
	v_mov_b32_e32 v22, v10
	v_mov_b32_e32 v23, v14
	v_mov_b32_e32 v14, v11
	v_pk_add_f32 v[10:11], v[22:23], v[14:15]
	v_mov_b32_e32 v14, v12
	v_mov_b32_e32 v15, v16
	v_mov_b32_e32 v16, v13
	v_mov_b32_e32 v12, v2
	v_mov_b32_e32 v13, v6
	v_mov_b32_e32 v6, v3
	v_pk_add_f32 v[10:11], v[14:15], v[10:11]
	v_pk_add_f32 v[2:3], v[12:13], v[6:7]
	v_mov_b32_e32 v6, v4
	v_mov_b32_e32 v7, v8
	v_pk_add_f32 v[10:11], v[16:17], v[10:11]
	v_pk_add_f32 v[2:3], v[6:7], v[2:3]
	v_mov_b32_e32 v8, v5
	v_pk_add_f32 v[2:3], v[8:9], v[2:3]
	v_add_f32_e32 v0, v10, v11
	v_add_f32_e32 v0, v0, v2
	v_lshl_add_u64 v[6:7], v[80:81], 0, v[20:21]
	v_lshl_add_u64 v[8:9], v[82:83], 0, v[94:95]
	v_add_f32_e32 v0, v0, v3
	global_load_dwordx4 v[50:53], v[6:7], off offset:16
	global_load_dwordx4 v[54:57], v[6:7], off
	global_load_dwordx4 v[2:5], v[8:9], off
	v_fmamk_f32 v0, v0, 0x3a800000, v198
	v_cmp_gt_f32_e32 vcc, s3, v0
	s_waitcnt vmcnt(0)
	v_lshlrev_b32_e32 v128, 16, v2
	v_and_b32_e32 v129, 0xffff0000, v2
	v_lshlrev_b32_e32 v132, 16, v3
	v_and_b32_e32 v133, 0xffff0000, v3
	v_lshlrev_b32_e32 v130, 16, v4
	v_and_b32_e32 v131, 0xffff0000, v4
	v_lshlrev_b32_e32 v134, 16, v5
	v_and_b32_e32 v135, 0xffff0000, v5
	global_load_dwordx4 v[22:25], v[6:7], off offset:2064
	global_load_dwordx4 v[30:33], v[6:7], off offset:2048
	global_load_dwordx4 v[2:5], v[8:9], off offset:1024
	s_waitcnt vmcnt(0)
	v_lshlrev_b32_e32 v98, 16, v2
	v_and_b32_e32 v99, 0xffff0000, v2
	v_lshlrev_b32_e32 v102, 16, v3
	v_and_b32_e32 v103, 0xffff0000, v3
	v_lshlrev_b64 v[2:3], 6, v[86:87]
	v_lshl_add_u64 v[14:15], s[66:67], 0, v[2:3]
	v_lshlrev_b32_e32 v96, 16, v4
	v_and_b32_e32 v97, 0xffff0000, v4
	v_lshlrev_b32_e32 v100, 16, v5
	v_and_b32_e32 v101, 0xffff0000, v5
	global_load_dwordx4 v[2:5], v[14:15], off offset:32
	global_load_dwordx4 v[6:9], v[14:15], off offset:48
	global_load_dwordx4 v[10:13], v[14:15], off
	s_nop 0
	global_load_dwordx4 v[14:17], v[14:15], off offset:16
	s_waitcnt vmcnt(0)
	v_mov_b32_e32 v20, v10
	v_mov_b32_e32 v21, v14
	v_mov_b32_e32 v14, v11
	v_pk_add_f32 v[10:11], v[20:21], v[14:15]
	v_mov_b32_e32 v14, v12
	v_mov_b32_e32 v15, v16
	v_pk_add_f32 v[10:11], v[14:15], v[10:11]
	v_mov_b32_e32 v16, v13
	v_pk_add_f32 v[166:167], v[16:17], v[10:11]
	v_mov_b32_e32 v10, v2
	v_mov_b32_e32 v11, v6
	v_mov_b32_e32 v6, v3
	v_pk_add_f32 v[2:3], v[10:11], v[6:7]
	v_mov_b32_e32 v6, v4
	v_mov_b32_e32 v7, v8
	v_pk_add_f32 v[2:3], v[6:7], v[2:3]
	v_mov_b32_e32 v8, v5
	v_pk_add_f32 v[168:169], v[8:9], v[2:3]
	v_lshl_add_u64 v[6:7], v[80:81], 0, v[18:19]
	v_lshl_add_u64 v[8:9], v[82:83], 0, v[92:93]
	global_load_dwordx4 v[42:45], v[6:7], off offset:16
	global_load_dwordx4 v[46:49], v[6:7], off
	global_load_dwordx4 v[2:5], v[8:9], off
	v_add_u32_e32 v18, 1, v86
	v_ashrrev_i32_e32 v19, 31, v18
	v_lshlrev_b64 v[20:21], 12, v[18:19]
	v_lshlrev_b64 v[90:91], 11, v[18:19]
	s_waitcnt vmcnt(0)
	v_lshlrev_b32_e32 v160, 16, v2
	v_and_b32_e32 v161, 0xffff0000, v2
	v_lshlrev_b32_e32 v164, 16, v3
	v_and_b32_e32 v165, 0xffff0000, v3
	v_lshlrev_b32_e32 v158, 16, v4
	v_and_b32_e32 v159, 0xffff0000, v4
	v_lshlrev_b32_e32 v162, 16, v5
	v_and_b32_e32 v163, 0xffff0000, v5
	global_load_dwordx4 v[34:37], v[6:7], off offset:2064
	global_load_dwordx4 v[38:41], v[6:7], off offset:2048
	global_load_dwordx4 v[2:5], v[8:9], off offset:1024
	s_waitcnt vmcnt(0)
	v_lshlrev_b32_e32 v104, 16, v2
	v_and_b32_e32 v105, 0xffff0000, v2
	v_lshlrev_b32_e32 v156, 16, v3
	v_and_b32_e32 v157, 0xffff0000, v3
	v_lshlrev_b64 v[2:3], 6, v[18:19]
	v_lshl_add_u64 v[14:15], s[66:67], 0, v[2:3]
	v_lshlrev_b32_e32 v106, 16, v4
	v_and_b32_e32 v107, 0xffff0000, v4
	v_lshlrev_b32_e32 v154, 16, v5
	v_and_b32_e32 v155, 0xffff0000, v5
	global_load_dwordx4 v[2:5], v[14:15], off offset:32
	global_load_dwordx4 v[6:9], v[14:15], off offset:48
	global_load_dwordx4 v[10:13], v[14:15], off
	s_nop 0
	global_load_dwordx4 v[14:17], v[14:15], off offset:16
	v_add_u32_e32 v18, 2, v86
	v_ashrrev_i32_e32 v19, 31, v18
	v_lshlrev_b64 v[88:89], 11, v[18:19]
	v_add_u32_e32 v86, s34, v86
	s_waitcnt vmcnt(0)
	v_mov_b32_e32 v26, v10
	v_mov_b32_e32 v27, v14
	v_mov_b32_e32 v14, v11
	v_pk_add_f32 v[10:11], v[26:27], v[14:15]
	v_mov_b32_e32 v14, v12
	v_mov_b32_e32 v15, v16
	v_pk_add_f32 v[10:11], v[14:15], v[10:11]
	v_mov_b32_e32 v16, v13
	v_pk_add_f32 v[186:187], v[16:17], v[10:11]
	v_mov_b32_e32 v10, v2
	v_mov_b32_e32 v11, v6
	v_mov_b32_e32 v6, v3
	v_pk_add_f32 v[2:3], v[10:11], v[6:7]
	v_mov_b32_e32 v6, v4
	v_mov_b32_e32 v7, v8
	v_pk_add_f32 v[2:3], v[6:7], v[2:3]
	v_mov_b32_e32 v8, v5
	v_pk_add_f32 v[188:189], v[8:9], v[2:3]
	v_lshl_add_u64 v[6:7], v[80:81], 0, v[20:21]
	v_lshl_add_u64 v[8:9], v[82:83], 0, v[90:91]
	global_load_dwordx4 v[66:69], v[6:7], off offset:16
	global_load_dwordx4 v[70:73], v[6:7], off
	global_load_dwordx4 v[2:5], v[8:9], off
	v_lshlrev_b64 v[20:21], 12, v[18:19]
	s_waitcnt vmcnt(0)
	v_lshlrev_b32_e32 v180, 16, v2
	v_and_b32_e32 v181, 0xffff0000, v2
	v_lshlrev_b32_e32 v184, 16, v3
	v_and_b32_e32 v185, 0xffff0000, v3
	v_lshlrev_b32_e32 v178, 16, v4
	v_and_b32_e32 v179, 0xffff0000, v4
	v_lshlrev_b32_e32 v182, 16, v5
	v_and_b32_e32 v183, 0xffff0000, v5
	global_load_dwordx4 v[58:61], v[6:7], off offset:2064
	global_load_dwordx4 v[62:65], v[6:7], off offset:2048
	global_load_dwordx4 v[2:5], v[8:9], off offset:1024
	s_waitcnt vmcnt(0)
	v_lshlrev_b32_e32 v172, 16, v2
	v_and_b32_e32 v173, 0xffff0000, v2
	v_lshlrev_b32_e32 v176, 16, v3
	v_and_b32_e32 v177, 0xffff0000, v3
	v_lshlrev_b64 v[2:3], 6, v[18:19]
	v_lshl_add_u64 v[14:15], s[66:67], 0, v[2:3]
	v_lshlrev_b32_e32 v170, 16, v4
	v_and_b32_e32 v171, 0xffff0000, v4
	v_lshlrev_b32_e32 v174, 16, v5
	v_and_b32_e32 v175, 0xffff0000, v5
	global_load_dwordx4 v[2:5], v[14:15], off offset:32
	global_load_dwordx4 v[6:9], v[14:15], off offset:48
	global_load_dwordx4 v[10:13], v[14:15], off
	s_nop 0
	global_load_dwordx4 v[14:17], v[14:15], off offset:16
	v_lshl_add_u64 v[18:19], v[82:83], 0, v[88:89]
	s_waitcnt vmcnt(0)
	v_mov_b32_e32 v26, v10
	v_mov_b32_e32 v27, v14
	v_mov_b32_e32 v14, v11
	v_pk_add_f32 v[10:11], v[26:27], v[14:15]
	v_mov_b32_e32 v14, v12
	v_mov_b32_e32 v15, v16
	v_pk_add_f32 v[10:11], v[14:15], v[10:11]
	v_mov_b32_e32 v16, v13
	v_pk_add_f32 v[116:117], v[16:17], v[10:11]
	v_mov_b32_e32 v10, v2
	v_mov_b32_e32 v11, v6
	v_mov_b32_e32 v6, v3
	v_pk_add_f32 v[2:3], v[10:11], v[6:7]
	v_mov_b32_e32 v6, v4
	v_mov_b32_e32 v7, v8
	v_pk_add_f32 v[2:3], v[6:7], v[2:3]
	v_mov_b32_e32 v8, v5
	v_lshl_add_u64 v[6:7], v[80:81], 0, v[20:21]
	v_pk_add_f32 v[126:127], v[8:9], v[2:3]
	global_load_dwordx4 v[10:13], v[6:7], off offset:16
	global_load_dwordx4 v[14:17], v[6:7], off
	global_load_dwordx4 v[2:5], v[18:19], off
	s_waitcnt vmcnt(0)
	v_lshlrev_b32_e32 v120, 16, v2
	v_and_b32_e32 v121, 0xffff0000, v2
	v_lshlrev_b32_e32 v124, 16, v3
	v_and_b32_e32 v125, 0xffff0000, v3
	v_lshlrev_b32_e32 v118, 16, v4
	v_and_b32_e32 v119, 0xffff0000, v4
	v_lshlrev_b32_e32 v122, 16, v5
	v_and_b32_e32 v123, 0xffff0000, v5
	global_load_dwordx4 v[2:5], v[6:7], off offset:2064
	s_nop 0
	global_load_dwordx4 v[6:9], v[6:7], off offset:2048
	s_nop 0
	global_load_dwordx4 v[18:21], v[18:19], off offset:1024
	s_waitcnt vmcnt(0)
	v_lshlrev_b32_e32 v110, 16, v18
	v_and_b32_e32 v111, 0xffff0000, v18
	v_mul_f32_e32 v18, 0x4b800000, v0
	v_cndmask_b32_e32 v0, v0, v18, vcc
	v_rsq_f32_e32 v0, v0
	v_lshlrev_b32_e32 v114, 16, v19
	v_and_b32_e32 v115, 0xffff0000, v19
	v_lshlrev_b32_e32 v108, 16, v20
	v_mul_f32_e32 v18, 0x45800000, v0
	v_and_b32_e32 v109, 0xffff0000, v20
	v_lshlrev_b32_e32 v112, 16, v21
	v_and_b32_e32 v113, 0xffff0000, v21
	v_cndmask_b32_e32 v0, v0, v18, vcc
	global_load_dwordx4 v[18:21], v[74:75], off offset:16
	global_load_dwordx4 v[26:29], v[74:75], off
	v_pk_mul_f32 v[136:137], v[0:1], v[128:129] op_sel_hi:[0,1]
	v_pk_mul_f32 v[128:129], v[0:1], v[132:133] op_sel_hi:[0,1]
	v_pk_mul_f32 v[98:99], v[0:1], v[98:99] op_sel_hi:[0,1]
	v_pk_mul_f32 v[102:103], v[0:1], v[102:103] op_sel_hi:[0,1]
	s_waitcnt vmcnt(0)
	v_pk_fma_f32 v[132:133], v[136:137], v[26:27], v[54:55]
	v_pk_mul_f32 v[54:55], v[0:1], v[130:131] op_sel_hi:[0,1]
	v_pk_fma_f32 v[128:129], v[128:129], v[28:29], v[56:57]
	v_pk_mul_f32 v[56:57], v[0:1], v[134:135] op_sel_hi:[0,1]
	v_pk_fma_f32 v[134:135], v[54:55], v[18:19], v[50:51]
	v_pk_fma_f32 v[130:131], v[56:57], v[20:21], v[52:53]
	v_mov_b32_e32 v52, v133
	v_mov_b32_e32 v53, v135
	v_mov_b32_e32 v50, v132
	v_mov_b32_e32 v51, v134
	v_pk_mul_f32 v[52:53], v[52:53], v[52:53]
	s_nop 0
	v_pk_fma_f32 v[50:51], v[50:51], v[50:51], v[52:53]
	v_mov_b32_e32 v52, v128
	v_mov_b32_e32 v53, v130
	v_pk_fma_f32 v[50:51], v[52:53], v[52:53], v[50:51]
	v_mov_b32_e32 v52, v129
	v_mov_b32_e32 v53, v131
	v_pk_fma_f32 v[206:207], v[52:53], v[52:53], v[50:51]
	global_load_dwordx4 v[50:53], v[74:75], off offset:2064
	global_load_dwordx4 v[54:57], v[74:75], off offset:2048
	s_waitcnt vmcnt(0)
	v_pk_fma_f32 v[140:141], v[98:99], v[54:55], v[30:31]
	v_pk_mul_f32 v[30:31], v[0:1], v[96:97] op_sel_hi:[0,1]
	v_pk_fma_f32 v[136:137], v[102:103], v[56:57], v[32:33]
	v_pk_mul_f32 v[32:33], v[0:1], v[100:101] op_sel_hi:[0,1]
	v_pk_fma_f32 v[142:143], v[30:31], v[50:51], v[22:23]
	v_pk_fma_f32 v[138:139], v[32:33], v[52:53], v[24:25]
	v_mov_b32_e32 v24, v141
	v_mov_b32_e32 v25, v143
	v_mov_b32_e32 v22, v140
	v_mov_b32_e32 v23, v142
	v_pk_mul_f32 v[24:25], v[24:25], v[24:25]
	v_add_f32_e32 v0, v206, v207
	v_pk_fma_f32 v[22:23], v[22:23], v[22:23], v[24:25]
	v_mov_b32_e32 v24, v136
	v_mov_b32_e32 v25, v138
	v_pk_fma_f32 v[22:23], v[24:25], v[24:25], v[22:23]
	v_mov_b32_e32 v24, v137
	v_mov_b32_e32 v25, v139
	v_pk_fma_f32 v[22:23], v[24:25], v[24:25], v[22:23]
	v_mov_b32_e32 v30, v188
	v_add_f32_e32 v0, v0, v22
	v_add_f32_e32 v24, v0, v23
	v_mov_b32_e32 v22, v186
	v_mov_b32_e32 v23, v166
	v_mov_b32_e32 v166, v187
	v_pk_add_f32 v[22:23], v[22:23], v[166:167]
	v_mov_b32_e32 v31, v168
	v_pk_add_f32 v[22:23], v[22:23], v[30:31]
	v_mov_b32_e32 v168, v189
	v_pk_add_f32 v[30:31], v[22:23], v[168:169]
	v_mov_b64_e32 v[22:23], s[38:39]
	v_pk_fma_f32 v[30:31], v[30:31], s[24:25], v[22:23] op_sel_hi:[1,0,0]
	s_nop 0
	v_mul_f32_e32 v0, 0x4b800000, v31
	v_cmp_gt_f32_e64 s[0:1], s3, v31
	v_cmp_gt_f32_e32 vcc, s3, v30
	s_nop 0
	v_cndmask_b32_e64 v0, v31, v0, s[0:1]
	v_rsq_f32_e32 v0, v0
	s_nop 0
	v_mul_f32_e32 v25, 0x45800000, v0
	v_cndmask_b32_e64 v0, v0, v25, s[0:1]
	v_pk_mul_f32 v[32:33], v[0:1], v[160:161] op_sel_hi:[0,1]
	v_pk_mul_f32 v[96:97], v[0:1], v[164:165] op_sel_hi:[0,1]
	v_pk_fma_f32 v[48:49], v[96:97], v[28:29], v[48:49]
	v_pk_fma_f32 v[96:97], v[32:33], v[26:27], v[46:47]
	v_pk_mul_f32 v[32:33], v[0:1], v[158:159] op_sel_hi:[0,1]
	v_pk_fma_f32 v[98:99], v[32:33], v[18:19], v[42:43]
	v_pk_mul_f32 v[46:47], v[0:1], v[162:163] op_sel_hi:[0,1]
	v_mov_b32_e32 v42, v97
	v_mov_b32_e32 v43, v99
	v_pk_fma_f32 v[46:47], v[46:47], v[20:21], v[44:45]
	v_mov_b32_e32 v32, v96
	v_mov_b32_e32 v33, v98
	v_pk_mul_f32 v[42:43], v[42:43], v[42:43]
	v_pk_mul_f32 v[44:45], v[0:1], v[156:157] op_sel_hi:[0,1]
	v_pk_fma_f32 v[32:33], v[32:33], v[32:33], v[42:43]
	v_mov_b32_e32 v42, v48
	v_mov_b32_e32 v43, v46
	v_pk_fma_f32 v[32:33], v[42:43], v[42:43], v[32:33]
	v_mov_b32_e32 v42, v49
	v_mov_b32_e32 v43, v47
	v_pk_fma_f32 v[32:33], v[42:43], v[42:43], v[32:33]
	v_pk_mul_f32 v[42:43], v[0:1], v[104:105] op_sel_hi:[0,1]
	v_pk_fma_f32 v[104:105], v[42:43], v[54:55], v[38:39]
	v_pk_mul_f32 v[38:39], v[0:1], v[106:107] op_sel_hi:[0,1]
	v_pk_fma_f32 v[100:101], v[44:45], v[56:57], v[40:41]
	v_pk_mul_f32 v[40:41], v[0:1], v[154:155] op_sel_hi:[0,1]
	v_pk_fma_f32 v[106:107], v[38:39], v[50:51], v[34:35]
	v_pk_fma_f32 v[102:103], v[40:41], v[52:53], v[36:37]
	v_mov_b32_e32 v36, v105
	v_mov_b32_e32 v37, v107
	v_mov_b32_e32 v34, v104
	v_mov_b32_e32 v35, v106
	v_pk_mul_f32 v[36:37], v[36:37], v[36:37]
	v_add_f32_e32 v0, v32, v33
	v_pk_fma_f32 v[34:35], v[34:35], v[34:35], v[36:37]
	v_mov_b32_e32 v36, v100
	v_mov_b32_e32 v37, v102
	v_pk_fma_f32 v[34:35], v[36:37], v[36:37], v[34:35]
	v_mov_b32_e32 v36, v101
	v_mov_b32_e32 v37, v103
	v_pk_fma_f32 v[34:35], v[36:37], v[36:37], v[34:35]
	s_nop 0
	v_add_f32_e32 v0, v0, v34
	v_add_f32_e32 v87, v0, v35
	v_mul_f32_e32 v0, 0x4b800000, v30
	v_cndmask_b32_e32 v0, v30, v0, vcc
	v_rsq_f32_e32 v0, v0
	s_nop 0
	v_mul_f32_e32 v25, 0x45800000, v0
	v_cndmask_b32_e32 v0, v0, v25, vcc
	v_pk_mul_f32 v[32:33], v[0:1], v[180:181] op_sel_hi:[0,1]
	v_pk_mul_f32 v[36:37], v[0:1], v[178:179] op_sel_hi:[0,1]
	v_pk_fma_f32 v[34:35], v[32:33], v[26:27], v[70:71]
	v_pk_fma_f32 v[36:37], v[36:37], v[18:19], v[66:67]
	v_pk_mul_f32 v[30:31], v[0:1], v[184:185] op_sel_hi:[0,1]
	v_pk_mul_f32 v[32:33], v[0:1], v[182:183] op_sel_hi:[0,1]
	v_mov_b32_e32 v40, v35
	v_mov_b32_e32 v41, v37
	v_pk_fma_f32 v[30:31], v[30:31], v[28:29], v[72:73]
	v_pk_fma_f32 v[32:33], v[32:33], v[20:21], v[68:69]
	v_mov_b32_e32 v38, v34
	v_mov_b32_e32 v39, v36
	v_pk_mul_f32 v[40:41], v[40:41], v[40:41]
	v_pk_mul_f32 v[44:45], v[0:1], v[170:171] op_sel_hi:[0,1]
	v_pk_fma_f32 v[38:39], v[38:39], v[38:39], v[40:41]
	v_mov_b32_e32 v40, v30
	v_mov_b32_e32 v41, v32
	v_pk_fma_f32 v[38:39], v[40:41], v[40:41], v[38:39]
	v_mov_b32_e32 v40, v31
	v_mov_b32_e32 v41, v33
	v_pk_fma_f32 v[66:67], v[40:41], v[40:41], v[38:39]
	v_pk_mul_f32 v[40:41], v[0:1], v[172:173] op_sel_hi:[0,1]
	v_pk_fma_f32 v[42:43], v[40:41], v[54:55], v[62:63]
	v_pk_mul_f32 v[40:41], v[0:1], v[174:175] op_sel_hi:[0,1]
	v_pk_fma_f32 v[44:45], v[44:45], v[50:51], v[58:59]
	v_pk_mul_f32 v[38:39], v[0:1], v[176:177] op_sel_hi:[0,1]
	v_pk_fma_f32 v[40:41], v[40:41], v[52:53], v[60:61]
	v_mov_b32_e32 v60, v43
	v_mov_b32_e32 v61, v45
	v_pk_fma_f32 v[38:39], v[38:39], v[56:57], v[64:65]
	v_mov_b32_e32 v58, v42
	v_mov_b32_e32 v59, v44
	v_pk_mul_f32 v[60:61], v[60:61], v[60:61]
	v_add_f32_e32 v0, v66, v67
	v_pk_fma_f32 v[58:59], v[58:59], v[58:59], v[60:61]
	v_mov_b32_e32 v60, v38
	v_mov_b32_e32 v61, v40
	v_pk_fma_f32 v[58:59], v[60:61], v[60:61], v[58:59]
	v_mov_b32_e32 v60, v39
	v_mov_b32_e32 v61, v41
	v_pk_fma_f32 v[58:59], v[60:61], v[60:61], v[58:59]
	v_lshl_add_u64 v[62:63], v[76:77], 0, v[94:95]
	v_add_f32_e32 v0, v0, v58
	v_cvt_pk_bf16_f32 v58, v132, v133
	v_add_f32_e32 v0, v0, v59
	v_cvt_pk_bf16_f32 v59, v128, v129
	v_cvt_pk_bf16_f32 v60, v134, v135
	v_cvt_pk_bf16_f32 v61, v130, v131
	global_store_dwordx4 v[62:63], v[58:61], off
	v_and_b32_e32 v25, 64, v199
	v_add_u32_e32 v25, 64, v25
	v_cvt_pk_bf16_f32 v58, v140, v141
	v_cvt_pk_bf16_f32 v59, v136, v137
	v_cvt_pk_bf16_f32 v60, v142, v143
	v_cvt_pk_bf16_f32 v61, v138, v139
	global_store_dwordx4 v[62:63], v[58:61], off offset:1024
	v_xor_b32_e32 v62, 2, v199
	v_xor_b32_e32 v63, 1, v199
	v_xor_b32_e32 v58, 32, v199
	v_cmp_lt_i32_e32 vcc, v58, v25
	v_mov_b32_e32 v65, v117
	s_nop 0
	v_cndmask_b32_e32 v58, v199, v58, vcc
	v_lshlrev_b32_e32 v58, 2, v58
	v_mov_b32_e32 v59, v24
	s_nop 1
	v_permlane32_swap_b32_e32 v59, v24
	s_waitcnt lgkmcnt(0)
	v_add_f32_e32 v24, v24, v59
	v_xor_b32_e32 v59, 16, v199
	v_cmp_lt_i32_e32 vcc, v59, v25
	s_nop 1
	v_cndmask_b32_e32 v59, v199, v59, vcc
	v_lshlrev_b32_e32 v59, 2, v59
	ds_bpermute_b32 v60, v59, v24
	s_waitcnt lgkmcnt(0)
	v_add_f32_e32 v24, v24, v60
	v_xor_b32_e32 v60, 8, v199
	v_cmp_lt_i32_e32 vcc, v60, v25
	s_nop 1
	v_cndmask_b32_e32 v60, v199, v60, vcc
	v_lshlrev_b32_e32 v60, 2, v60
	s_nop 1
	v_mov_b32_dpp v61, v24 row_ror:8 row_mask:0xf bank_mask:0xf bound_ctrl:0
	s_waitcnt lgkmcnt(0)
	v_add_f32_e32 v24, v24, v61
	v_xor_b32_e32 v61, 4, v199
	v_cmp_lt_i32_e32 vcc, v61, v25
	s_nop 1
	v_cndmask_b32_e32 v61, v199, v61, vcc
	v_lshlrev_b32_e32 v61, 2, v61
	s_nop 1
	v_mov_b32_dpp v64, v24 row_half_mirror row_mask:0xf bank_mask:0xf bound_ctrl:0
	v_cmp_lt_i32_e32 vcc, v62, v25
	s_nop 1
	v_cndmask_b32_e32 v62, v199, v62, vcc
	v_cmp_lt_i32_e32 vcc, v63, v25
	v_lshlrev_b32_e32 v62, 2, v62
	s_nop 0
	v_cndmask_b32_e32 v25, v199, v63, vcc
	v_lshlrev_b32_e32 v63, 2, v25
	v_mov_b32_e32 v25, v116
	s_waitcnt lgkmcnt(0)
	v_pk_add_f32 v[24:25], v[24:25], v[64:65]
	s_nop 1
	v_mov_b32_dpp v64, v24 quad_perm:[2,3,0,1] row_mask:0xf bank_mask:0xf bound_ctrl:0
	v_mov_b32_e32 v65, v126
	s_waitcnt lgkmcnt(0)
	v_pk_add_f32 v[24:25], v[24:25], v[64:65]
	s_nop 1
	v_mov_b32_dpp v126, v24 quad_perm:[1,0,3,2] row_mask:0xf bank_mask:0xf bound_ctrl:0
	s_waitcnt lgkmcnt(0)
	v_pk_add_f32 v[24:25], v[24:25], v[126:127]
	s_nop 0
	v_pk_fma_f32 v[64:65], v[24:25], s[24:25], v[22:23] op_sel_hi:[1,0,0]
	s_nop 0
	v_mul_f32_e32 v22, 0x4b800000, v65
	v_cmp_gt_f32_e64 s[0:1], s3, v65
	v_cmp_gt_f32_e32 vcc, s3, v64
	s_nop 0
	v_cndmask_b32_e64 v22, v65, v22, s[0:1]
	v_rsq_f32_e32 v22, v22
	s_nop 0
	v_mul_f32_e32 v23, 0x45800000, v22
	v_cndmask_b32_e64 v66, v22, v23, s[0:1]
	v_pk_mul_f32 v[24:25], v[66:67], v[120:121] op_sel_hi:[0,1]
	v_pk_mul_f32 v[22:23], v[66:67], v[124:125] op_sel_hi:[0,1]
	v_pk_fma_f32 v[24:25], v[26:27], v[24:25], v[14:15]
	v_pk_mul_f32 v[14:15], v[66:67], v[118:119] op_sel_hi:[0,1]
	v_pk_fma_f32 v[22:23], v[28:29], v[22:23], v[16:17]
	v_pk_mul_f32 v[16:17], v[66:67], v[122:123] op_sel_hi:[0,1]
	v_pk_fma_f32 v[18:19], v[18:19], v[14:15], v[10:11]
	v_pk_fma_f32 v[20:21], v[20:21], v[16:17], v[12:13]
	v_mov_b32_e32 v12, v25
	v_mov_b32_e32 v13, v19
	v_mov_b32_e32 v10, v24
	v_mov_b32_e32 v11, v18
	v_pk_mul_f32 v[12:13], v[12:13], v[12:13]
	s_nop 0
	v_pk_fma_f32 v[10:11], v[10:11], v[10:11], v[12:13]
	v_mov_b32_e32 v12, v22
	v_mov_b32_e32 v13, v20
	v_pk_fma_f32 v[10:11], v[12:13], v[12:13], v[10:11]
	v_mov_b32_e32 v12, v23
	v_mov_b32_e32 v13, v21
	v_pk_fma_f32 v[26:27], v[12:13], v[12:13], v[10:11]
	v_pk_mul_f32 v[12:13], v[66:67], v[110:111] op_sel_hi:[0,1]
	v_pk_mul_f32 v[10:11], v[66:67], v[114:115] op_sel_hi:[0,1]
	v_pk_fma_f32 v[14:15], v[54:55], v[12:13], v[6:7]
	v_pk_mul_f32 v[6:7], v[66:67], v[108:109] op_sel_hi:[0,1]
	v_pk_fma_f32 v[10:11], v[56:57], v[10:11], v[8:9]
	v_pk_mul_f32 v[8:9], v[66:67], v[112:113] op_sel_hi:[0,1]
	v_pk_fma_f32 v[16:17], v[50:51], v[6:7], v[2:3]
	v_pk_fma_f32 v[12:13], v[52:53], v[8:9], v[4:5]
	v_mov_b32_e32 v4, v17
	v_mov_b32_e32 v5, v15
	v_mov_b32_e32 v2, v16
	v_mov_b32_e32 v3, v14
	v_pk_mul_f32 v[4:5], v[4:5], v[4:5]
	v_lshl_add_u64 v[50:51], v[84:85], 0, v[94:95]
	v_pk_fma_f32 v[2:3], v[2:3], v[2:3], v[4:5]
	v_mov_b32_e32 v4, v12
	v_mov_b32_e32 v5, v10
	v_pk_fma_f32 v[2:3], v[4:5], v[4:5], v[2:3]
	v_mov_b32_e32 v4, v13
	v_mov_b32_e32 v5, v11
	v_pk_fma_f32 v[2:3], v[4:5], v[4:5], v[2:3]
	v_add_f32_e32 v4, v26, v27
	v_add_f32_e32 v3, v3, v4
	v_add_f32_e32 v2, v2, v3
	v_mul_f32_e32 v3, 0x4b800000, v64
	v_cndmask_b32_e32 v3, v64, v3, vcc
	v_rsq_f32_e32 v3, v3
	s_nop 0
	v_mul_f32_e32 v4, 0x45800000, v3
	v_cndmask_b32_e32 v8, v3, v4, vcc
	global_load_dwordx4 v[4:7], v[78:79], off offset:16
	global_load_dwordx4 v[26:29], v[78:79], off
	v_pk_mul_f32 v[52:53], v[132:133], v[8:9] op_sel_hi:[1,0]
	v_pk_mul_f32 v[54:55], v[128:129], v[8:9] op_sel_hi:[1,0]
	ds_bpermute_b32 v3, v58, v87
	s_waitcnt lgkmcnt(0)
	v_add_f32_e32 v3, v87, v3
	s_waitcnt vmcnt(0)
	v_pk_mul_f32 v[28:29], v[28:29], v[54:55]
	v_pk_mul_f32 v[26:27], v[26:27], v[52:53]
	v_pk_mul_f32 v[52:53], v[134:135], v[8:9] op_sel_hi:[1,0]
	v_pk_mul_f32 v[54:55], v[130:131], v[8:9] op_sel_hi:[1,0]
	s_nop 0
	v_pk_mul_f32 v[54:55], v[6:7], v[54:55]
	v_pk_mul_f32 v[6:7], v[4:5], v[52:53]
	v_cvt_pk_bf16_f32 v4, v26, v27
	v_cvt_pk_bf16_f32 v5, v28, v29
	v_pk_mul_f32 v[52:53], v[140:141], v[8:9] op_sel_hi:[1,0]
	v_cvt_pk_bf16_f32 v6, v6, v7
	v_cvt_pk_bf16_f32 v7, v54, v55
	global_store_dwordx4 v[50:51], v[4:7], off
	global_load_dwordx4 v[4:7], v[78:79], off offset:2064
	s_nop 0
	global_load_dwordx4 v[26:29], v[78:79], off offset:2048
	v_pk_mul_f32 v[54:55], v[136:137], v[8:9] op_sel_hi:[1,0]
	s_waitcnt vmcnt(0)
	v_pk_mul_f32 v[26:27], v[26:27], v[52:53]
	v_pk_mul_f32 v[52:53], v[142:143], v[8:9] op_sel_hi:[1,0]
	v_pk_mul_f32 v[8:9], v[138:139], v[8:9] op_sel_hi:[1,0]
	v_pk_mul_f32 v[28:29], v[28:29], v[54:55]
	v_pk_mul_f32 v[8:9], v[6:7], v[8:9]
	v_pk_mul_f32 v[6:7], v[4:5], v[52:53]
	v_cvt_pk_bf16_f32 v4, v26, v27
	v_cvt_pk_bf16_f32 v5, v28, v29
	s_nop 0
	v_cvt_pk_bf16_f32 v6, v6, v7
	v_cvt_pk_bf16_f32 v7, v8, v9
	global_store_dwordx4 v[50:51], v[4:7], off offset:1024
	v_lshl_add_u64 v[8:9], v[76:77], 0, v[92:93]
	v_lshl_add_u64 v[50:51], v[84:85], 0, v[92:93]
	v_cvt_pk_bf16_f32 v4, v96, v97
	v_cvt_pk_bf16_f32 v5, v48, v49
	v_cvt_pk_bf16_f32 v6, v98, v99
	v_cvt_pk_bf16_f32 v7, v46, v47
	global_store_dwordx4 v[8:9], v[4:7], off
	s_nop 1
	v_cvt_pk_bf16_f32 v4, v104, v105
	v_cvt_pk_bf16_f32 v5, v100, v101
	v_cvt_pk_bf16_f32 v6, v106, v107
	v_cvt_pk_bf16_f32 v7, v102, v103
	global_store_dwordx4 v[8:9], v[4:7], off offset:1024
	ds_bpermute_b32 v4, v59, v3
	s_waitcnt lgkmcnt(0)
	v_add_f32_e32 v3, v3, v4
	s_nop 1
	v_mov_b32_dpp v4, v3 row_ror:8 row_mask:0xf bank_mask:0xf bound_ctrl:0
	s_waitcnt lgkmcnt(0)
	v_add_f32_e32 v3, v3, v4
	s_nop 1
	v_mov_b32_dpp v4, v3 row_half_mirror row_mask:0xf bank_mask:0xf bound_ctrl:0
	s_waitcnt lgkmcnt(0)
	v_add_f32_e32 v3, v3, v4
	s_nop 1
	v_mov_b32_dpp v4, v3 quad_perm:[2,3,0,1] row_mask:0xf bank_mask:0xf bound_ctrl:0
	s_waitcnt lgkmcnt(0)
	v_add_f32_e32 v3, v3, v4
	s_nop 1
	v_mov_b32_dpp v4, v3 quad_perm:[1,0,3,2] row_mask:0xf bank_mask:0xf bound_ctrl:0
	s_waitcnt lgkmcnt(0)
	v_add_f32_e32 v3, v3, v4
	v_fmamk_f32 v3, v3, 0x3a800000, v198
	v_cmp_gt_f32_e32 vcc, s3, v3
	v_mul_f32_e32 v4, 0x4b800000, v3
	s_nop 0
	v_cndmask_b32_e32 v3, v3, v4, vcc
	v_rsq_f32_e32 v3, v3
	s_nop 0
	v_mul_f32_e32 v4, 0x45800000, v3
	v_cndmask_b32_e32 v8, v3, v4, vcc
	global_load_dwordx4 v[4:7], v[78:79], off offset:16
	global_load_dwordx4 v[26:29], v[78:79], off
	v_pk_mul_f32 v[48:49], v[48:49], v[8:9] op_sel_hi:[1,0]
	v_pk_mul_f32 v[46:47], v[46:47], v[8:9] op_sel_hi:[1,0]
	v_pk_mul_f32 v[52:53], v[96:97], v[8:9] op_sel_hi:[1,0]
	v_mov_b32_e32 v3, v0
	s_nop 1
	v_permlane32_swap_b32_e32 v3, v0
	s_waitcnt lgkmcnt(0)
	v_add_f32_e32 v0, v0, v3
	ds_bpermute_b32 v3, v59, v0
	s_waitcnt lgkmcnt(0)
	v_add_f32_e32 v0, v0, v3
	s_nop 1
	v_mov_b32_dpp v3, v0 row_ror:8 row_mask:0xf bank_mask:0xf bound_ctrl:0
	s_waitcnt lgkmcnt(0)
	v_add_f32_e32 v0, v0, v3
	s_nop 1
	v_mov_b32_dpp v3, v0 row_half_mirror row_mask:0xf bank_mask:0xf bound_ctrl:0
	s_waitcnt lgkmcnt(0)
	v_add_f32_e32 v0, v0, v3
	s_nop 1
	v_mov_b32_dpp v3, v0 quad_perm:[2,3,0,1] row_mask:0xf bank_mask:0xf bound_ctrl:0
	s_waitcnt lgkmcnt(0)
	v_add_f32_e32 v0, v0, v3
	s_nop 1
	v_mov_b32_dpp v3, v0 quad_perm:[1,0,3,2] row_mask:0xf bank_mask:0xf bound_ctrl:0
	s_waitcnt lgkmcnt(0)
	v_add_f32_e32 v0, v0, v3
	v_fmamk_f32 v0, v0, 0x3a800000, v198
	v_cmp_gt_f32_e32 vcc, s3, v0
	v_mul_f32_e32 v3, 0x4b800000, v0
	s_waitcnt vmcnt(1)
	v_pk_mul_f32 v[46:47], v[6:7], v[46:47]
	s_waitcnt vmcnt(0)
	v_pk_mul_f32 v[28:29], v[28:29], v[48:49]
	v_pk_mul_f32 v[48:49], v[98:99], v[8:9] op_sel_hi:[1,0]
	v_pk_mul_f32 v[26:27], v[26:27], v[52:53]
	v_pk_mul_f32 v[6:7], v[4:5], v[48:49]
	v_cvt_pk_bf16_f32 v4, v26, v27
	v_cvt_pk_bf16_f32 v5, v28, v29
	v_pk_mul_f32 v[48:49], v[100:101], v[8:9] op_sel_hi:[1,0]
	v_cvt_pk_bf16_f32 v6, v6, v7
	v_cvt_pk_bf16_f32 v7, v46, v47
	global_store_dwordx4 v[50:51], v[4:7], off
	global_load_dwordx4 v[4:7], v[78:79], off offset:2064
	s_nop 0
	global_load_dwordx4 v[26:29], v[78:79], off offset:2048
	v_pk_mul_f32 v[46:47], v[104:105], v[8:9] op_sel_hi:[1,0]
	v_cndmask_b32_e32 v0, v0, v3, vcc
	v_rsq_f32_e32 v0, v0
	s_waitcnt vmcnt(0)
	v_pk_mul_f32 v[26:27], v[26:27], v[46:47]
	v_pk_mul_f32 v[46:47], v[106:107], v[8:9] op_sel_hi:[1,0]
	v_pk_mul_f32 v[8:9], v[102:103], v[8:9] op_sel_hi:[1,0]
	v_pk_mul_f32 v[28:29], v[28:29], v[48:49]
	v_pk_mul_f32 v[8:9], v[6:7], v[8:9]
	v_pk_mul_f32 v[6:7], v[4:5], v[46:47]
	v_cvt_pk_bf16_f32 v4, v26, v27
	v_cvt_pk_bf16_f32 v5, v28, v29
	v_mul_f32_e32 v3, 0x45800000, v0
	v_cvt_pk_bf16_f32 v6, v6, v7
	v_cvt_pk_bf16_f32 v7, v8, v9
	global_store_dwordx4 v[50:51], v[4:7], off offset:1024
	v_lshl_add_u64 v[8:9], v[76:77], 0, v[90:91]
	v_cndmask_b32_e32 v0, v0, v3, vcc
	v_cvt_pk_bf16_f32 v4, v34, v35
	v_cvt_pk_bf16_f32 v5, v30, v31
	v_cvt_pk_bf16_f32 v6, v36, v37
	v_cvt_pk_bf16_f32 v7, v32, v33
	global_store_dwordx4 v[8:9], v[4:7], off
	v_pk_mul_f32 v[30:31], v[30:31], v[0:1] op_sel_hi:[1,0]
	v_pk_mul_f32 v[32:33], v[32:33], v[0:1] op_sel_hi:[1,0]
	v_cvt_pk_bf16_f32 v4, v42, v43
	v_cvt_pk_bf16_f32 v5, v38, v39
	v_cvt_pk_bf16_f32 v6, v44, v45
	v_cvt_pk_bf16_f32 v7, v40, v41
	global_store_dwordx4 v[8:9], v[4:7], off offset:1024
	global_load_dwordx4 v[4:7], v[78:79], off offset:16
	s_nop 0
	global_load_dwordx4 v[26:29], v[78:79], off
	v_lshl_add_u64 v[8:9], v[84:85], 0, v[90:91]
	v_pk_mul_f32 v[34:35], v[34:35], v[0:1] op_sel_hi:[1,0]
	s_waitcnt vmcnt(1)
	v_pk_mul_f32 v[32:33], v[6:7], v[32:33]
	s_waitcnt vmcnt(0)
	v_pk_mul_f32 v[28:29], v[28:29], v[30:31]
	v_pk_mul_f32 v[30:31], v[36:37], v[0:1] op_sel_hi:[1,0]
	v_pk_mul_f32 v[26:27], v[26:27], v[34:35]
	v_pk_mul_f32 v[6:7], v[4:5], v[30:31]
	v_cvt_pk_bf16_f32 v4, v26, v27
	v_cvt_pk_bf16_f32 v5, v28, v29
	v_pk_mul_f32 v[30:31], v[42:43], v[0:1] op_sel_hi:[1,0]
	v_cvt_pk_bf16_f32 v6, v6, v7
	v_cvt_pk_bf16_f32 v7, v32, v33
	global_store_dwordx4 v[8:9], v[4:7], off
	global_load_dwordx4 v[4:7], v[78:79], off offset:2064
	s_nop 0
	global_load_dwordx4 v[26:29], v[78:79], off offset:2048
	v_pk_mul_f32 v[32:33], v[38:39], v[0:1] op_sel_hi:[1,0]
	s_waitcnt vmcnt(0)
	v_pk_mul_f32 v[26:27], v[26:27], v[30:31]
	v_pk_mul_f32 v[28:29], v[28:29], v[32:33]
	v_pk_mul_f32 v[30:31], v[44:45], v[0:1] op_sel_hi:[1,0]
	v_pk_mul_f32 v[32:33], v[40:41], v[0:1] op_sel_hi:[1,0]
	v_mov_b32_e32 v0, v2
	s_nop 1
	v_permlane32_swap_b32_e32 v0, v2
	v_pk_mul_f32 v[32:33], v[6:7], v[32:33]
	v_pk_mul_f32 v[6:7], v[4:5], v[30:31]
	v_cvt_pk_bf16_f32 v4, v26, v27
	v_cvt_pk_bf16_f32 v5, v28, v29
	s_waitcnt lgkmcnt(0)
	v_add_f32_e32 v0, v2, v0
	ds_bpermute_b32 v2, v59, v0
	v_cvt_pk_bf16_f32 v6, v6, v7
	v_cvt_pk_bf16_f32 v7, v32, v33
	global_store_dwordx4 v[8:9], v[4:7], off offset:1024
	v_lshl_add_u64 v[8:9], v[76:77], 0, v[88:89]
	s_waitcnt lgkmcnt(0)
	v_add_f32_e32 v0, v0, v2
	s_nop 1
	v_mov_b32_dpp v2, v0 row_ror:8 row_mask:0xf bank_mask:0xf bound_ctrl:0
	v_cvt_pk_bf16_f32 v4, v24, v25
	v_cvt_pk_bf16_f32 v5, v22, v23
	v_cvt_pk_bf16_f32 v6, v18, v19
	v_cvt_pk_bf16_f32 v7, v20, v21
	s_waitcnt lgkmcnt(0)
	v_add_f32_e32 v0, v0, v2
	s_nop 1
	v_mov_b32_dpp v2, v0 row_half_mirror row_mask:0xf bank_mask:0xf bound_ctrl:0
	global_store_dwordx4 v[8:9], v[4:7], off
	v_lshl_add_u64 v[26:27], v[84:85], 0, v[88:89]
	s_waitcnt lgkmcnt(0)
	v_add_f32_e32 v0, v0, v2
	ds_bpermute_b32 v2, v62, v0
	v_cvt_pk_bf16_f32 v4, v14, v15
	v_cvt_pk_bf16_f32 v5, v10, v11
	v_cvt_pk_bf16_f32 v6, v16, v17
	v_cvt_pk_bf16_f32 v7, v12, v13
	s_waitcnt lgkmcnt(0)
	v_add_f32_e32 v0, v0, v2
	ds_bpermute_b32 v2, v63, v0
	global_store_dwordx4 v[8:9], v[4:7], off offset:1024
	s_waitcnt lgkmcnt(0)
	v_add_f32_e32 v0, v0, v2
	v_fmamk_f32 v0, v0, 0x3a800000, v198
	v_cmp_gt_f32_e32 vcc, s3, v0
	v_mul_f32_e32 v2, 0x4b800000, v0
	s_nop 0
	v_cndmask_b32_e32 v0, v0, v2, vcc
	v_rsq_f32_e32 v0, v0
	s_nop 0
	v_mul_f32_e32 v2, 0x45800000, v0
	v_cndmask_b32_e32 v0, v0, v2, vcc
	global_load_dwordx4 v[2:5], v[78:79], off offset:16
	global_load_dwordx4 v[6:9], v[78:79], off
	v_pk_mul_f32 v[18:19], v[18:19], v[0:1] op_sel_hi:[1,0]
	v_pk_mul_f32 v[20:21], v[20:21], v[0:1] op_sel_hi:[1,0]
	v_pk_mul_f32 v[24:25], v[24:25], v[0:1] op_sel_hi:[1,0]
	v_pk_mul_f32 v[22:23], v[22:23], v[0:1] op_sel_hi:[1,0]
	v_pk_mul_f32 v[10:11], v[10:11], v[0:1] op_sel_hi:[1,0]
	v_pk_mul_f32 v[12:13], v[12:13], v[0:1] op_sel_hi:[1,0]
	v_cmp_le_i32_e32 vcc, s25, v192
	v_pk_mul_f32 v[14:15], v[14:15], v[0:1] op_sel_hi:[1,0]
	s_or_b64 s[6:7], vcc, s[6:7]
	s_waitcnt vmcnt(1)
	v_pk_mul_f32 v[20:21], v[4:5], v[20:21]
	v_pk_mul_f32 v[4:5], v[2:3], v[18:19]
	s_waitcnt vmcnt(0)
	v_pk_mul_f32 v[8:9], v[8:9], v[22:23]
	v_pk_mul_f32 v[6:7], v[6:7], v[24:25]
	s_nop 0
	v_cvt_pk_bf16_f32 v2, v6, v7
	v_cvt_pk_bf16_f32 v3, v8, v9
	v_cvt_pk_bf16_f32 v4, v4, v5
	v_cvt_pk_bf16_f32 v5, v20, v21
	global_store_dwordx4 v[26:27], v[2:5], off
	global_load_dwordx4 v[2:5], v[78:79], off offset:2064
	s_nop 0
	global_load_dwordx4 v[6:9], v[78:79], off offset:2048
	s_waitcnt vmcnt(1)
	v_pk_mul_f32 v[12:13], v[4:5], v[12:13]
	s_waitcnt vmcnt(0)
	v_pk_mul_f32 v[8:9], v[8:9], v[10:11]
	v_pk_mul_f32 v[10:11], v[16:17], v[0:1] op_sel_hi:[1,0]
	v_pk_mul_f32 v[6:7], v[6:7], v[14:15]
	v_pk_mul_f32 v[4:5], v[2:3], v[10:11]
	v_cvt_pk_bf16_f32 v2, v6, v7
	v_cvt_pk_bf16_f32 v3, v8, v9
	s_nop 0
	v_cvt_pk_bf16_f32 v4, v4, v5
	v_cvt_pk_bf16_f32 v5, v12, v13
	global_store_dwordx4 v[26:27], v[2:5], off offset:1024
	s_andn2_b64 exec, exec, s[6:7]
	s_cbranch_execnz .LBB0_388

.LBB0_391:
	v_lshl_add_u64 v[30:31], s[86:87], 0, v[26:27]
	v_add_co_u32_e32 v32, vcc, 0x4080000, v30
	global_load_dwordx4 v[10:13], v[28:29], off offset:-2032
	global_load_dwordx4 v[14:17], v[28:29], off offset:-2048
	v_addc_co_u32_e32 v33, vcc, 0, v31, vcc
	global_load_dwordx4 v[2:5], v[32:33], off
	v_lshl_add_u64 v[48:49], s[86:87], 0, v[24:25]
	v_lshl_add_u64 v[60:61], v[48:49], 0, s[14:15]
	v_add_co_u32_e32 v48, vcc, s10, v48
	v_add_u32_e32 v18, s6, v18
	s_nop 0
	v_addc_co_u32_e32 v49, vcc, 0, v49, vcc
	v_lshl_add_u64 v[24:25], v[24:25], 0, s[64:65]
	v_lshl_add_u64 v[26:27], v[26:27], 0, s[92:93]
	s_waitcnt vmcnt(0)
	v_lshlrev_b32_e32 v42, 16, v2
	v_and_b32_e32 v43, 0xffff0000, v2
	v_lshlrev_b32_e32 v46, 16, v3
	v_and_b32_e32 v47, 0xffff0000, v3
	v_lshlrev_b32_e32 v40, 16, v4
	v_and_b32_e32 v41, 0xffff0000, v4
	v_lshlrev_b32_e32 v44, 16, v5
	v_and_b32_e32 v45, 0xffff0000, v5
	global_load_dwordx4 v[2:5], v[28:29], off offset:16
	global_load_dwordx4 v[6:9], v[28:29], off
	global_load_dwordx4 v[34:37], v[32:33], off offset:1024
	s_nop 0
	global_load_dwordx4 v[48:51], v[48:49], off
	s_nop 0
	global_load_dwordx4 v[52:55], v[60:61], off offset:32
	global_load_dwordx4 v[56:59], v[60:61], off offset:48
	s_nop 0
	global_load_dwordx4 v[60:63], v[60:61], off offset:16
	v_lshl_add_u64 v[28:29], v[28:29], 0, s[8:9]
	s_waitcnt vmcnt(0)
	v_mov_b32_e32 v64, v48
	v_lshlrev_b32_e32 v32, 16, v34
	v_mov_b32_e32 v65, v60
	v_mov_b32_e32 v60, v49
	v_pk_add_f32 v[48:49], v[64:65], v[60:61]
	v_mov_b32_e32 v60, v50
	v_mov_b32_e32 v61, v62
	v_mov_b32_e32 v62, v51
	v_mov_b32_e32 v50, v52
	v_mov_b32_e32 v51, v56
	v_mov_b32_e32 v56, v53
	v_pk_add_f32 v[48:49], v[60:61], v[48:49]
	v_pk_add_f32 v[50:51], v[50:51], v[56:57]
	v_mov_b32_e32 v52, v54
	v_mov_b32_e32 v53, v58
	v_pk_add_f32 v[48:49], v[62:63], v[48:49]
	v_pk_add_f32 v[50:51], v[52:53], v[50:51]
	v_mov_b32_e32 v58, v55
	v_pk_add_f32 v[50:51], v[58:59], v[50:51]
	v_add_f32_e32 v0, v48, v49
	v_add_f32_e32 v0, v0, v50
	v_add_f32_e32 v0, v0, v51
	global_load_dwordx4 v[48:51], v[20:21], off offset:16
	global_load_dwordx4 v[52:55], v[20:21], off
	v_fmamk_f32 v0, v0, 0x3a800000, v198
	v_cmp_gt_f32_e32 vcc, s7, v0
	v_mul_f32_e32 v19, 0x4b800000, v0
	v_and_b32_e32 v33, 0xffff0000, v34
	v_cndmask_b32_e32 v0, v0, v19, vcc
	v_rsq_f32_e32 v0, v0
	v_lshlrev_b32_e32 v38, 16, v35
	v_and_b32_e32 v39, 0xffff0000, v35
	v_lshlrev_b32_e32 v34, 16, v36
	v_mul_f32_e32 v19, 0x45800000, v0
	v_cndmask_b32_e32 v0, v0, v19, vcc
	v_pk_mul_f32 v[42:43], v[0:1], v[42:43] op_sel_hi:[0,1]
	v_pk_mul_f32 v[40:41], v[0:1], v[40:41] op_sel_hi:[0,1]
	v_pk_mul_f32 v[46:47], v[0:1], v[46:47] op_sel_hi:[0,1]
	v_and_b32_e32 v35, 0xffff0000, v36
	v_lshlrev_b32_e32 v36, 16, v37
	v_and_b32_e32 v37, 0xffff0000, v37
	v_pk_mul_f32 v[32:33], v[0:1], v[32:33] op_sel_hi:[0,1]
	v_pk_mul_f32 v[34:35], v[0:1], v[34:35] op_sel_hi:[0,1]
	v_pk_mul_f32 v[38:39], v[0:1], v[38:39] op_sel_hi:[0,1]
	s_waitcnt vmcnt(0)
	v_pk_fma_f32 v[10:11], v[48:49], v[40:41], v[10:11]
	v_pk_fma_f32 v[14:15], v[52:53], v[42:43], v[14:15]
	v_pk_mul_f32 v[42:43], v[0:1], v[44:45] op_sel_hi:[0,1]
	v_pk_fma_f32 v[12:13], v[50:51], v[42:43], v[12:13]
	v_mov_b32_e32 v42, v15
	v_mov_b32_e32 v43, v11
	v_pk_fma_f32 v[16:17], v[54:55], v[46:47], v[16:17]
	v_mov_b32_e32 v40, v14
	v_mov_b32_e32 v41, v10
	v_pk_mul_f32 v[42:43], v[42:43], v[42:43]
	s_nop 0
	v_pk_fma_f32 v[40:41], v[40:41], v[40:41], v[42:43]
	v_mov_b32_e32 v42, v16
	v_mov_b32_e32 v43, v12
	v_pk_fma_f32 v[40:41], v[42:43], v[42:43], v[40:41]
	v_mov_b32_e32 v42, v17
	v_mov_b32_e32 v43, v13
	v_pk_fma_f32 v[48:49], v[42:43], v[42:43], v[40:41]
	global_load_dwordx4 v[40:43], v[20:21], off offset:2064
	global_load_dwordx4 v[44:47], v[20:21], off offset:2048
	s_waitcnt vmcnt(0)
	v_pk_fma_f32 v[34:35], v[40:41], v[34:35], v[2:3]
	v_pk_fma_f32 v[32:33], v[44:45], v[32:33], v[6:7]
	v_pk_mul_f32 v[6:7], v[0:1], v[36:37] op_sel_hi:[0,1]
	v_pk_fma_f32 v[6:7], v[42:43], v[6:7], v[4:5]
	v_mov_b32_e32 v4, v35
	v_mov_b32_e32 v5, v33
	v_pk_fma_f32 v[8:9], v[46:47], v[38:39], v[8:9]
	v_mov_b32_e32 v2, v34
	v_mov_b32_e32 v3, v32
	v_pk_mul_f32 v[4:5], v[4:5], v[4:5]
	v_add_f32_e32 v0, v48, v49
	v_pk_fma_f32 v[2:3], v[2:3], v[2:3], v[4:5]
	v_mov_b32_e32 v4, v6
	v_mov_b32_e32 v5, v8
	v_pk_fma_f32 v[2:3], v[4:5], v[4:5], v[2:3]
	v_mov_b32_e32 v4, v7
	v_mov_b32_e32 v5, v9
	v_pk_fma_f32 v[2:3], v[4:5], v[4:5], v[2:3]
	v_add_co_u32_e32 v36, vcc, s11, v30
	v_add_f32_e32 v0, v3, v0
	v_add_f32_e32 v0, v2, v0
	v_cvt_pk_bf16_f32 v2, v14, v15
	v_addc_co_u32_e32 v37, vcc, 0, v31, vcc
	v_cvt_pk_bf16_f32 v3, v16, v17
	v_cvt_pk_bf16_f32 v4, v10, v11
	v_cvt_pk_bf16_f32 v5, v12, v13
	global_store_dwordx4 v[36:37], v[2:5], off
	s_nop 1
	v_cvt_pk_bf16_f32 v2, v32, v33
	v_cvt_pk_bf16_f32 v3, v8, v9
	v_cvt_pk_bf16_f32 v4, v34, v35
	v_cvt_pk_bf16_f32 v5, v6, v7
	global_store_dwordx4 v[36:37], v[2:5], off offset:1024
	s_nop 1
	v_and_b32_e32 v2, 64, v199
	v_add_u32_e32 v2, 64, v2
	v_xor_b32_e32 v3, 32, v199
	v_cmp_lt_i32_e32 vcc, v3, v2
	s_nop 1
	v_cndmask_b32_e32 v3, v199, v3, vcc
	v_lshlrev_b32_e32 v3, 2, v3
	v_mov_b32_e32 v3, v0
	s_nop 1
	v_permlane32_swap_b32_e32 v3, v0
	s_waitcnt lgkmcnt(0)
	v_add_f32_e32 v0, v0, v3
	v_xor_b32_e32 v3, 16, v199
	v_cmp_lt_i32_e32 vcc, v3, v2
	s_nop 1
	v_cndmask_b32_e32 v3, v199, v3, vcc
	v_lshlrev_b32_e32 v3, 2, v3
	ds_bpermute_b32 v3, v3, v0
	s_waitcnt lgkmcnt(0)
	v_add_f32_e32 v0, v0, v3
	v_xor_b32_e32 v3, 8, v199
	v_cmp_lt_i32_e32 vcc, v3, v2
	s_nop 1
	v_cndmask_b32_e32 v3, v199, v3, vcc
	v_lshlrev_b32_e32 v3, 2, v3
	s_nop 1
	v_mov_b32_dpp v3, v0 row_ror:8 row_mask:0xf bank_mask:0xf bound_ctrl:0
	s_waitcnt lgkmcnt(0)
	v_add_f32_e32 v0, v0, v3
	v_xor_b32_e32 v3, 4, v199
	v_cmp_lt_i32_e32 vcc, v3, v2
	s_nop 1
	v_cndmask_b32_e32 v3, v199, v3, vcc
	v_lshlrev_b32_e32 v3, 2, v3
	s_nop 1
	v_mov_b32_dpp v3, v0 row_half_mirror row_mask:0xf bank_mask:0xf bound_ctrl:0
	s_waitcnt lgkmcnt(0)
	v_add_f32_e32 v0, v0, v3
	v_xor_b32_e32 v3, 2, v199
	v_cmp_lt_i32_e32 vcc, v3, v2
	s_nop 1
	v_cndmask_b32_e32 v3, v199, v3, vcc
	v_lshlrev_b32_e32 v3, 2, v3
	s_nop 1
	v_mov_b32_dpp v3, v0 quad_perm:[2,3,0,1] row_mask:0xf bank_mask:0xf bound_ctrl:0
	s_waitcnt lgkmcnt(0)
	v_add_f32_e32 v0, v0, v3
	v_xor_b32_e32 v3, 1, v199
	v_cmp_lt_i32_e32 vcc, v3, v2
	s_nop 1
	v_cndmask_b32_e32 v2, v199, v3, vcc
	v_lshlrev_b32_e32 v2, 2, v2
	s_nop 1
	v_mov_b32_dpp v2, v0 quad_perm:[1,0,3,2] row_mask:0xf bank_mask:0xf bound_ctrl:0
	s_waitcnt lgkmcnt(0)
	v_add_f32_e32 v0, v0, v2
	v_fmamk_f32 v0, v0, 0x3a800000, v198
	v_cmp_gt_f32_e32 vcc, s7, v0
	v_mul_f32_e32 v2, 0x4b800000, v0
	s_nop 0
	v_cndmask_b32_e32 v0, v0, v2, vcc
	v_rsq_f32_e32 v0, v0
	s_nop 0
	v_mul_f32_e32 v2, 0x45800000, v0
	v_cndmask_b32_e32 v0, v0, v2, vcc
	global_load_dwordx4 v[2:5], v[22:23], off offset:16
	global_load_dwordx4 v[36:39], v[22:23], off
	v_pk_mul_f32 v[10:11], v[10:11], v[0:1] op_sel_hi:[1,0]
	v_pk_mul_f32 v[12:13], v[12:13], v[0:1] op_sel_hi:[1,0]
	v_pk_mul_f32 v[14:15], v[14:15], v[0:1] op_sel_hi:[1,0]
	v_pk_mul_f32 v[16:17], v[16:17], v[0:1] op_sel_hi:[1,0]
	v_pk_mul_f32 v[8:9], v[8:9], v[0:1] op_sel_hi:[1,0]
	v_pk_mul_f32 v[6:7], v[6:7], v[0:1] op_sel_hi:[1,0]
	v_cmp_lt_i32_e32 vcc, s12, v18
	s_or_b64 s[4:5], vcc, s[4:5]
	s_waitcnt vmcnt(1)
	v_pk_mul_f32 v[12:13], v[4:5], v[12:13]
	v_pk_mul_f32 v[4:5], v[2:3], v[10:11]
	s_waitcnt vmcnt(0)
	v_pk_mul_f32 v[16:17], v[38:39], v[16:17]
	v_pk_mul_f32 v[14:15], v[36:37], v[14:15]
	s_nop 0
	v_cvt_pk_bf16_f32 v2, v14, v15
	v_cvt_pk_bf16_f32 v3, v16, v17
	v_cvt_pk_bf16_f32 v4, v4, v5
	v_cvt_pk_bf16_f32 v5, v12, v13
	global_store_dwordx4 v[30:31], v[2:5], off
	global_load_dwordx4 v[2:5], v[22:23], off offset:2064
	s_nop 0
	global_load_dwordx4 v[10:13], v[22:23], off offset:2048
	v_pk_mul_f32 v[14:15], v[32:33], v[0:1] op_sel_hi:[1,0]
	s_waitcnt vmcnt(1)
	v_pk_mul_f32 v[6:7], v[4:5], v[6:7]
	s_waitcnt vmcnt(0)
	v_pk_mul_f32 v[8:9], v[12:13], v[8:9]
	v_pk_mul_f32 v[12:13], v[34:35], v[0:1] op_sel_hi:[1,0]
	v_pk_mul_f32 v[10:11], v[10:11], v[14:15]
	v_pk_mul_f32 v[4:5], v[2:3], v[12:13]
	v_cvt_pk_bf16_f32 v2, v10, v11
	v_cvt_pk_bf16_f32 v3, v8, v9
	s_nop 0
	v_cvt_pk_bf16_f32 v4, v4, v5
	v_cvt_pk_bf16_f32 v5, v6, v7
	global_store_dwordx4 v[30:31], v[2:5], off offset:1024
	s_andn2_b64 exec, exec, s[4:5]
	s_cbranch_execnz .LBB0_391

.LBB0_410:
	v_add_u32_e32 v48, 0x8000, v47
	v_cmp_gt_i32_e32 vcc, s94, v48
	v_mov_b32_e32 v4, s11
	v_mov_b32_e32 v5, s9
	v_cndmask_b32_e32 v3, 0, v19, vcc
	v_cndmask_b32_e32 v2, v47, v18, vcc
	v_cndmask_b32_e32 v5, v4, v5, vcc
	v_mov_b32_e32 v4, s10
	v_mov_b32_e32 v6, s8
	v_cndmask_b32_e32 v4, v4, v6, vcc
	v_lshlrev_b64 v[2:3], 12, v[2:3]
	v_lshl_add_u64 v[28:29], s[86:87], 0, v[26:27]
	v_lshl_add_u64 v[2:3], v[4:5], 0, v[2:3]
	v_add_co_u32_e32 v30, vcc, s7, v28
	v_lshl_add_u64 v[6:7], v[2:3], 0, v[0:1]
	s_nop 0
	v_addc_co_u32_e32 v31, vcc, 0, v29, vcc
	global_load_dwordx4 v[10:13], v[6:7], off offset:16
	global_load_dwordx4 v[14:17], v[6:7], off
	global_load_dwordx4 v[2:5], v[30:31], off
	v_lshl_add_u64 v[50:51], s[86:87], 0, v[24:25]
	v_lshl_add_u64 v[62:63], v[50:51], 0, s[16:17]
	v_add_co_u32_e32 v50, vcc, s12, v50
	v_lshl_add_u64 v[24:25], v[24:25], 0, s[18:19]
	s_nop 0
	v_addc_co_u32_e32 v51, vcc, 0, v51, vcc
	v_lshl_add_u64 v[26:27], v[26:27], 0, s[20:21]
	v_lshl_add_u64 v[18:19], v[18:19], 0, 32
	s_waitcnt vmcnt(0)
	v_lshlrev_b32_e32 v40, 16, v2
	v_and_b32_e32 v41, 0xffff0000, v2
	v_lshlrev_b32_e32 v44, 16, v3
	v_and_b32_e32 v45, 0xffff0000, v3
	v_lshlrev_b32_e32 v38, 16, v4
	v_and_b32_e32 v39, 0xffff0000, v4
	v_lshlrev_b32_e32 v42, 16, v5
	v_and_b32_e32 v43, 0xffff0000, v5
	global_load_dwordx4 v[2:5], v[6:7], off offset:2064
	s_nop 0
	global_load_dwordx4 v[6:9], v[6:7], off offset:2048
	s_nop 0
	global_load_dwordx4 v[32:35], v[30:31], off offset:1024
	s_nop 0
	global_load_dwordx4 v[50:53], v[50:51], off
	s_nop 0
	global_load_dwordx4 v[54:57], v[62:63], off offset:32
	global_load_dwordx4 v[58:61], v[62:63], off offset:48
	s_nop 0
	global_load_dwordx4 v[62:65], v[62:63], off offset:16
	s_waitcnt vmcnt(3)
	v_mov_b32_e32 v66, v50
	v_lshlrev_b32_e32 v30, 16, v32
	s_waitcnt vmcnt(0)
	v_mov_b32_e32 v67, v62
	v_mov_b32_e32 v62, v51
	v_pk_add_f32 v[50:51], v[66:67], v[62:63]
	v_mov_b32_e32 v62, v52
	v_mov_b32_e32 v63, v64
	v_mov_b32_e32 v64, v53
	v_mov_b32_e32 v52, v54
	v_mov_b32_e32 v53, v58
	v_mov_b32_e32 v58, v55
	v_pk_add_f32 v[50:51], v[62:63], v[50:51]
	v_pk_add_f32 v[52:53], v[52:53], v[58:59]
	v_mov_b32_e32 v54, v56
	v_mov_b32_e32 v55, v60
	v_pk_add_f32 v[50:51], v[64:65], v[50:51]
	v_pk_add_f32 v[52:53], v[54:55], v[52:53]
	v_mov_b32_e32 v60, v57
	v_pk_add_f32 v[52:53], v[60:61], v[52:53]
	v_add_f32_e32 v46, v50, v51
	v_add_f32_e32 v46, v46, v52
	v_add_f32_e32 v46, v46, v53
	global_load_dwordx4 v[50:53], v[20:21], off offset:16
	global_load_dwordx4 v[54:57], v[20:21], off
	v_fmamk_f32 v46, v46, 0x3a800000, v198
	v_cmp_gt_f32_e32 vcc, s6, v46
	v_mul_f32_e32 v49, 0x4b800000, v46
	v_and_b32_e32 v31, 0xffff0000, v32
	v_cndmask_b32_e32 v46, v46, v49, vcc
	v_rsq_f32_e32 v46, v46
	v_lshlrev_b32_e32 v36, 16, v33
	v_and_b32_e32 v37, 0xffff0000, v33
	v_lshlrev_b32_e32 v32, 16, v34
	v_mul_f32_e32 v49, 0x45800000, v46
	v_cndmask_b32_e32 v46, v46, v49, vcc
	v_pk_mul_f32 v[40:41], v[46:47], v[40:41] op_sel_hi:[0,1]
	v_pk_mul_f32 v[38:39], v[46:47], v[38:39] op_sel_hi:[0,1]
	v_pk_mul_f32 v[44:45], v[46:47], v[44:45] op_sel_hi:[0,1]
	v_and_b32_e32 v33, 0xffff0000, v34
	v_lshlrev_b32_e32 v34, 16, v35
	v_and_b32_e32 v35, 0xffff0000, v35
	v_pk_mul_f32 v[30:31], v[46:47], v[30:31] op_sel_hi:[0,1]
	v_pk_mul_f32 v[32:33], v[46:47], v[32:33] op_sel_hi:[0,1]
	v_pk_mul_f32 v[36:37], v[46:47], v[36:37] op_sel_hi:[0,1]
	s_waitcnt vmcnt(1)
	v_pk_fma_f32 v[10:11], v[50:51], v[38:39], v[10:11]
	s_waitcnt vmcnt(0)
	v_pk_fma_f32 v[14:15], v[54:55], v[40:41], v[14:15]
	v_pk_mul_f32 v[40:41], v[46:47], v[42:43] op_sel_hi:[0,1]
	v_pk_fma_f32 v[12:13], v[52:53], v[40:41], v[12:13]
	v_mov_b32_e32 v40, v15
	v_mov_b32_e32 v41, v11
	v_pk_fma_f32 v[16:17], v[56:57], v[44:45], v[16:17]
	v_mov_b32_e32 v38, v14
	v_mov_b32_e32 v39, v10
	v_pk_mul_f32 v[40:41], v[40:41], v[40:41]
	s_nop 0
	v_pk_fma_f32 v[38:39], v[38:39], v[38:39], v[40:41]
	v_mov_b32_e32 v40, v16
	v_mov_b32_e32 v41, v12
	v_pk_fma_f32 v[38:39], v[40:41], v[40:41], v[38:39]
	v_mov_b32_e32 v40, v17
	v_mov_b32_e32 v41, v13
	v_pk_fma_f32 v[50:51], v[40:41], v[40:41], v[38:39]
	global_load_dwordx4 v[38:41], v[20:21], off offset:2064
	global_load_dwordx4 v[42:45], v[20:21], off offset:2048
	s_waitcnt vmcnt(1)
	v_pk_fma_f32 v[32:33], v[38:39], v[32:33], v[2:3]
	s_waitcnt vmcnt(0)
	v_pk_fma_f32 v[30:31], v[42:43], v[30:31], v[6:7]
	v_pk_mul_f32 v[6:7], v[46:47], v[34:35] op_sel_hi:[0,1]
	v_pk_fma_f32 v[6:7], v[40:41], v[6:7], v[4:5]
	v_mov_b32_e32 v4, v33
	v_mov_b32_e32 v5, v31
	v_pk_fma_f32 v[8:9], v[44:45], v[36:37], v[8:9]
	v_mov_b32_e32 v2, v32
	v_mov_b32_e32 v3, v30
	v_pk_mul_f32 v[4:5], v[4:5], v[4:5]
	v_add_co_u32_e32 v34, vcc, s13, v28
	v_pk_fma_f32 v[2:3], v[2:3], v[2:3], v[4:5]
	v_mov_b32_e32 v4, v6
	v_mov_b32_e32 v5, v8
	v_pk_fma_f32 v[2:3], v[4:5], v[4:5], v[2:3]
	v_mov_b32_e32 v4, v7
	v_mov_b32_e32 v5, v9
	v_pk_fma_f32 v[2:3], v[4:5], v[4:5], v[2:3]
	v_add_f32_e32 v4, v50, v51
	v_add_f32_e32 v3, v3, v4
	v_add_f32_e32 v36, v2, v3
	v_cvt_pk_bf16_f32 v2, v14, v15
	v_addc_co_u32_e32 v35, vcc, 0, v29, vcc
	v_cvt_pk_bf16_f32 v3, v16, v17
	v_cvt_pk_bf16_f32 v4, v10, v11
	v_cvt_pk_bf16_f32 v5, v12, v13
	global_store_dwordx4 v[34:35], v[2:5], off
	v_add_u32_e32 v47, 32, v47
	s_nop 0
	v_cvt_pk_bf16_f32 v2, v30, v31
	v_cvt_pk_bf16_f32 v3, v8, v9
	v_cvt_pk_bf16_f32 v4, v32, v33
	v_cvt_pk_bf16_f32 v5, v6, v7
	global_store_dwordx4 v[34:35], v[2:5], off offset:1024
	s_nop 1
	v_and_b32_e32 v2, 64, v199
	v_add_u32_e32 v2, 64, v2
	v_xor_b32_e32 v3, 32, v199
	v_cmp_lt_i32_e32 vcc, v3, v2
	v_xor_b32_e32 v4, 16, v199
	s_nop 0
	v_cndmask_b32_e32 v3, v199, v3, vcc
	v_lshlrev_b32_e32 v3, 2, v3
	v_mov_b32_e32 v3, v36
	s_nop 1
	v_permlane32_swap_b32_e32 v3, v36
	v_cmp_lt_i32_e32 vcc, v4, v2
	s_waitcnt lgkmcnt(0)
	v_add_f32_e32 v3, v36, v3
	v_cndmask_b32_e32 v4, v199, v4, vcc
	v_lshlrev_b32_e32 v4, 2, v4
	ds_bpermute_b32 v4, v4, v3
	s_waitcnt lgkmcnt(0)
	v_add_f32_e32 v3, v3, v4
	v_xor_b32_e32 v4, 8, v199
	v_cmp_lt_i32_e32 vcc, v4, v2
	s_nop 1
	v_cndmask_b32_e32 v4, v199, v4, vcc
	v_lshlrev_b32_e32 v4, 2, v4
	s_nop 1
	v_mov_b32_dpp v4, v3 row_ror:8 row_mask:0xf bank_mask:0xf bound_ctrl:0
	s_waitcnt lgkmcnt(0)
	v_add_f32_e32 v3, v3, v4
	v_xor_b32_e32 v4, 4, v199
	v_cmp_lt_i32_e32 vcc, v4, v2
	s_nop 1
	v_cndmask_b32_e32 v4, v199, v4, vcc
	v_lshlrev_b32_e32 v4, 2, v4
	s_nop 1
	v_mov_b32_dpp v4, v3 row_half_mirror row_mask:0xf bank_mask:0xf bound_ctrl:0
	s_waitcnt lgkmcnt(0)
	v_add_f32_e32 v3, v3, v4
	v_xor_b32_e32 v4, 2, v199
	v_cmp_lt_i32_e32 vcc, v4, v2
	s_nop 1
	v_cndmask_b32_e32 v4, v199, v4, vcc
	v_lshlrev_b32_e32 v4, 2, v4
	s_nop 1
	v_mov_b32_dpp v4, v3 quad_perm:[2,3,0,1] row_mask:0xf bank_mask:0xf bound_ctrl:0
	s_waitcnt lgkmcnt(0)
	v_add_f32_e32 v3, v3, v4
	v_xor_b32_e32 v4, 1, v199
	v_cmp_lt_i32_e32 vcc, v4, v2
	s_nop 1
	v_cndmask_b32_e32 v2, v199, v4, vcc
	v_lshlrev_b32_e32 v2, 2, v2
	s_nop 1
	v_mov_b32_dpp v2, v3 quad_perm:[1,0,3,2] row_mask:0xf bank_mask:0xf bound_ctrl:0
	s_waitcnt lgkmcnt(0)
	v_add_f32_e32 v2, v3, v2
	v_fmamk_f32 v2, v2, 0x3a800000, v198
	v_cmp_gt_f32_e32 vcc, s6, v2
	v_mul_f32_e32 v3, 0x4b800000, v2
	s_nop 0
	v_cndmask_b32_e32 v2, v2, v3, vcc
	v_rsq_f32_e32 v2, v2
	s_nop 0
	v_mul_f32_e32 v3, 0x45800000, v2
	v_cndmask_b32_e32 v34, v2, v3, vcc
	global_load_dwordx4 v[2:5], v[22:23], off offset:16
	global_load_dwordx4 v[36:39], v[22:23], off
	v_pk_mul_f32 v[10:11], v[10:11], v[34:35] op_sel_hi:[1,0]
	v_pk_mul_f32 v[12:13], v[12:13], v[34:35] op_sel_hi:[1,0]
	v_pk_mul_f32 v[14:15], v[14:15], v[34:35] op_sel_hi:[1,0]
	v_pk_mul_f32 v[16:17], v[16:17], v[34:35] op_sel_hi:[1,0]
	v_pk_mul_f32 v[8:9], v[8:9], v[34:35] op_sel_hi:[1,0]
	v_pk_mul_f32 v[6:7], v[6:7], v[34:35] op_sel_hi:[1,0]
	v_cmp_lt_i32_e32 vcc, s14, v48
	s_or_b64 s[4:5], vcc, s[4:5]
	s_waitcnt vmcnt(1)
	v_pk_mul_f32 v[12:13], v[4:5], v[12:13]
	v_pk_mul_f32 v[4:5], v[2:3], v[10:11]
	s_waitcnt vmcnt(0)
	v_pk_mul_f32 v[16:17], v[38:39], v[16:17]
	v_pk_mul_f32 v[14:15], v[36:37], v[14:15]
	s_nop 0
	v_cvt_pk_bf16_f32 v2, v14, v15
	v_cvt_pk_bf16_f32 v3, v16, v17
	v_cvt_pk_bf16_f32 v4, v4, v5
	v_cvt_pk_bf16_f32 v5, v12, v13
	global_store_dwordx4 v[28:29], v[2:5], off
	global_load_dwordx4 v[2:5], v[22:23], off offset:2064
	s_nop 0
	global_load_dwordx4 v[10:13], v[22:23], off offset:2048
	v_pk_mul_f32 v[14:15], v[30:31], v[34:35] op_sel_hi:[1,0]
	s_waitcnt vmcnt(1)
	v_pk_mul_f32 v[6:7], v[4:5], v[6:7]
	s_waitcnt vmcnt(0)
	v_pk_mul_f32 v[8:9], v[12:13], v[8:9]
	v_pk_mul_f32 v[12:13], v[32:33], v[34:35] op_sel_hi:[1,0]
	v_pk_mul_f32 v[10:11], v[10:11], v[14:15]
	v_pk_mul_f32 v[4:5], v[2:3], v[12:13]
	v_cvt_pk_bf16_f32 v2, v10, v11
	v_cvt_pk_bf16_f32 v3, v8, v9
	s_nop 0
	v_cvt_pk_bf16_f32 v4, v4, v5
	v_cvt_pk_bf16_f32 v5, v6, v7
	global_store_dwordx4 v[28:29], v[2:5], off offset:1024
	s_andn2_b64 exec, exec, s[4:5]
	s_cbranch_execnz .LBB0_410

.LBB0_495:
	s_or_b64 exec, exec, s[0:1]
	v_cvt_pk_bf16_f32 v120, v110, v111
	v_mul_f32_e32 v111, v111, v111
	v_fmac_f32_e32 v111, v110, v110
	v_mul_f32_e32 v110, v103, v103
	v_fmac_f32_e32 v110, v102, v102
	v_fmac_f32_e32 v111, v112, v112
	v_fmac_f32_e32 v110, v104, v104
	v_fmac_f32_e32 v111, v113, v113
	v_fmac_f32_e32 v110, v105, v105
	v_fmac_f32_e32 v111, v106, v106
	v_fmac_f32_e32 v110, v98, v98
	v_fmac_f32_e32 v111, v107, v107
	v_fmac_f32_e32 v110, v99, v99
	v_fmac_f32_e32 v111, v108, v108
	v_fmac_f32_e32 v110, v100, v100
	v_or_b32_e32 v114, 16, v154
	v_fmac_f32_e32 v111, v109, v109
	v_fmac_f32_e32 v110, v101, v101
	v_ashrrev_i32_e32 v115, 31, v114
	v_add_f32_e32 v110, v111, v110
	v_lshlrev_b64 v[116:117], 11, v[114:115]
	ds_bpermute_b32 v111, v126, v110
	v_lshl_add_u64 v[116:117], s[78:79], 0, v[116:117]
	v_lshl_add_u64 v[116:117], s[62:63], 1, v[116:117]
	v_lshl_add_u64 v[116:117], v[116:117], 0, s[70:71]
	v_lshl_add_u64 v[116:117], v[116:117], 0, v[0:1]
	v_cvt_pk_bf16_f32 v121, v112, v113
	s_waitcnt lgkmcnt(0)
	v_cvt_pk_bf16_f32 v122, v106, v107
	v_cvt_pk_bf16_f32 v123, v108, v109
	global_store_dwordx4 v[116:117], v[120:123], off
	v_cvt_pk_bf16_f32 v106, v102, v103
	v_add_f32_e32 v102, v110, v111
	v_mov_b32_e32 v103, v102
	s_nop 1
	v_permlane32_swap_b32_e32 v103, v102
	v_cvt_pk_bf16_f32 v107, v104, v105
	v_cvt_pk_bf16_f32 v108, v98, v99
	v_cvt_pk_bf16_f32 v109, v100, v101
	global_store_dwordx4 v[116:117], v[106:109], off offset:256
	s_and_saveexec_b64 s[0:1], s[40:41]
	s_cbranch_execz .LBB0_497
	v_lshlrev_b64 v[98:99], 6, v[114:115]
	v_lshl_add_u64 v[98:99], s[66:67], 0, v[98:99]
	v_lshl_add_u64 v[98:99], s[60:61], 2, v[98:99]
	s_lshl_b32 s18, s21, 2
	s_mov_b32 s19, s71
	s_waitcnt lgkmcnt(0)
	v_add_f32_e32 v100, v102, v103
	v_lshl_add_u64 v[98:99], v[98:99], 0, s[18:19]
	global_store_dword v[98:99], v100, off
.LBB0_497:
	s_or_b64 exec, exec, s[0:1]
	v_or_b32_e32 v98, 32, v154
	v_ashrrev_i32_e32 v99, 31, v98
	v_lshlrev_b64 v[100:101], 11, v[98:99]
	v_lshl_add_u64 v[100:101], s[78:79], 0, v[100:101]
	v_lshl_add_u64 v[100:101], s[62:63], 1, v[100:101]
	v_lshl_add_u64 v[100:101], v[100:101], 0, s[70:71]
	v_lshl_add_u64 v[104:105], v[100:101], 0, v[0:1]
	v_cvt_pk_bf16_f32 v100, v94, v95
	v_mul_f32_e32 v95, v95, v95
	v_fmac_f32_e32 v95, v94, v94
	v_mul_f32_e32 v94, v87, v87
	v_fmac_f32_e32 v94, v86, v86
	v_fmac_f32_e32 v95, v96, v96
	v_fmac_f32_e32 v94, v88, v88
	v_fmac_f32_e32 v95, v97, v97
	v_fmac_f32_e32 v94, v89, v89
	v_fmac_f32_e32 v95, v90, v90
	v_fmac_f32_e32 v94, v82, v82
	v_fmac_f32_e32 v95, v91, v91
	v_fmac_f32_e32 v94, v83, v83
	v_fmac_f32_e32 v95, v92, v92
	v_fmac_f32_e32 v94, v84, v84
	v_fmac_f32_e32 v95, v93, v93
	v_fmac_f32_e32 v94, v85, v85
	v_add_f32_e32 v94, v95, v94
	ds_bpermute_b32 v95, v126, v94
	v_cvt_pk_bf16_f32 v101, v96, v97
	v_cvt_pk_bf16_f32 v102, v90, v91
	s_waitcnt lgkmcnt(0)
	v_cvt_pk_bf16_f32 v103, v92, v93
	global_store_dwordx4 v[104:105], v[100:103], off
	v_cvt_pk_bf16_f32 v90, v86, v87
	v_add_f32_e32 v86, v94, v95
	v_mov_b32_e32 v87, v86
	s_nop 1
	v_permlane32_swap_b32_e32 v87, v86
	v_cvt_pk_bf16_f32 v91, v88, v89
	v_cvt_pk_bf16_f32 v92, v82, v83
	v_cvt_pk_bf16_f32 v93, v84, v85
	global_store_dwordx4 v[104:105], v[90:93], off offset:256
	s_and_saveexec_b64 s[0:1], s[40:41]
	s_cbranch_execz .LBB0_499
	v_lshlrev_b64 v[82:83], 6, v[98:99]
	v_lshl_add_u64 v[82:83], s[66:67], 0, v[82:83]
	v_lshl_add_u64 v[82:83], s[60:61], 2, v[82:83]
	s_lshl_b32 s18, s21, 2
	s_mov_b32 s19, s71
	s_waitcnt lgkmcnt(0)
	v_add_f32_e32 v84, v86, v87
	v_lshl_add_u64 v[82:83], v[82:83], 0, s[18:19]
	global_store_dword v[82:83], v84, off
.LBB0_499:
	s_or_b64 exec, exec, s[0:1]
	v_or_b32_e32 v82, 48, v154
	v_ashrrev_i32_e32 v83, 31, v82
	v_lshlrev_b64 v[84:85], 11, v[82:83]
	v_lshl_add_u64 v[84:85], s[78:79], 0, v[84:85]
	v_lshl_add_u64 v[84:85], s[62:63], 1, v[84:85]
	v_lshl_add_u64 v[84:85], v[84:85], 0, s[70:71]
	v_lshl_add_u64 v[88:89], v[84:85], 0, v[0:1]
	v_cvt_pk_bf16_f32 v84, v78, v79
	v_mul_f32_e32 v79, v79, v79
	v_fmac_f32_e32 v79, v78, v78
	v_mul_f32_e32 v78, v71, v71
	v_fmac_f32_e32 v78, v70, v70
	v_fmac_f32_e32 v79, v80, v80
	v_fmac_f32_e32 v78, v72, v72
	v_fmac_f32_e32 v79, v81, v81
	v_fmac_f32_e32 v78, v73, v73
	v_fmac_f32_e32 v79, v74, v74
	v_fmac_f32_e32 v78, v66, v66
	v_fmac_f32_e32 v79, v75, v75
	v_fmac_f32_e32 v78, v67, v67
	v_fmac_f32_e32 v79, v76, v76
	v_fmac_f32_e32 v78, v68, v68
	v_fmac_f32_e32 v79, v77, v77
	v_fmac_f32_e32 v78, v69, v69
	v_add_f32_e32 v78, v79, v78
	ds_bpermute_b32 v79, v126, v78
	v_cvt_pk_bf16_f32 v85, v80, v81
	v_cvt_pk_bf16_f32 v86, v74, v75
	s_waitcnt lgkmcnt(0)
	v_cvt_pk_bf16_f32 v87, v76, v77
	global_store_dwordx4 v[88:89], v[84:87], off
	v_cvt_pk_bf16_f32 v74, v70, v71
	v_add_f32_e32 v70, v78, v79
	v_mov_b32_e32 v71, v70
	s_nop 1
	v_permlane32_swap_b32_e32 v71, v70
	v_cvt_pk_bf16_f32 v75, v72, v73
	v_cvt_pk_bf16_f32 v76, v66, v67
	v_cvt_pk_bf16_f32 v77, v68, v69
	global_store_dwordx4 v[88:89], v[74:77], off offset:256
	s_and_saveexec_b64 s[0:1], s[40:41]
	s_cbranch_execz .LBB0_501
	v_lshlrev_b64 v[66:67], 6, v[82:83]
	v_lshl_add_u64 v[66:67], s[66:67], 0, v[66:67]
	v_lshl_add_u64 v[66:67], s[60:61], 2, v[66:67]
	s_lshl_b32 s18, s21, 2
	s_mov_b32 s19, s71
	s_waitcnt lgkmcnt(0)
	v_add_f32_e32 v68, v70, v71
	v_lshl_add_u64 v[66:67], v[66:67], 0, s[18:19]
	global_store_dword v[66:67], v68, off
.LBB0_501:
	s_or_b64 exec, exec, s[0:1]
	v_add_u32_e32 v66, 0x80, v154
	v_ashrrev_i32_e32 v67, 31, v66
	v_lshlrev_b64 v[68:69], 11, v[66:67]
	v_lshl_add_u64 v[68:69], s[78:79], 0, v[68:69]
	v_lshl_add_u64 v[68:69], s[62:63], 1, v[68:69]
	v_lshl_add_u64 v[68:69], v[68:69], 0, s[70:71]
	v_lshl_add_u64 v[72:73], v[68:69], 0, v[0:1]
	v_cvt_pk_bf16_f32 v68, v62, v63
	v_mul_f32_e32 v63, v63, v63
	v_fmac_f32_e32 v63, v62, v62
	v_mul_f32_e32 v62, v55, v55
	v_fmac_f32_e32 v62, v54, v54
	v_fmac_f32_e32 v63, v64, v64
	v_fmac_f32_e32 v62, v56, v56
	v_fmac_f32_e32 v63, v65, v65
	v_fmac_f32_e32 v62, v57, v57
	v_fmac_f32_e32 v63, v58, v58
	v_fmac_f32_e32 v62, v50, v50
	v_fmac_f32_e32 v63, v59, v59
	v_fmac_f32_e32 v62, v51, v51
	v_fmac_f32_e32 v63, v60, v60
	v_fmac_f32_e32 v62, v52, v52
	v_fmac_f32_e32 v63, v61, v61
	v_fmac_f32_e32 v62, v53, v53
	v_add_f32_e32 v62, v63, v62
	ds_bpermute_b32 v63, v126, v62
	v_cvt_pk_bf16_f32 v69, v64, v65
	v_cvt_pk_bf16_f32 v70, v58, v59
	s_waitcnt lgkmcnt(0)
	v_cvt_pk_bf16_f32 v71, v60, v61
	global_store_dwordx4 v[72:73], v[68:71], off
	v_cvt_pk_bf16_f32 v58, v54, v55
	v_add_f32_e32 v54, v62, v63
	v_mov_b32_e32 v55, v54
	s_nop 1
	v_permlane32_swap_b32_e32 v55, v54
	v_cvt_pk_bf16_f32 v59, v56, v57
	v_cvt_pk_bf16_f32 v60, v50, v51
	v_cvt_pk_bf16_f32 v61, v52, v53
	global_store_dwordx4 v[72:73], v[58:61], off offset:256
	s_and_saveexec_b64 s[0:1], s[40:41]
	s_cbranch_execz .LBB0_503
	v_lshlrev_b64 v[50:51], 6, v[66:67]
	v_lshl_add_u64 v[50:51], s[66:67], 0, v[50:51]
	v_lshl_add_u64 v[50:51], s[60:61], 2, v[50:51]
	s_lshl_b32 s18, s21, 2
	s_mov_b32 s19, s71
	s_waitcnt lgkmcnt(0)
	v_add_f32_e32 v52, v54, v55
	v_lshl_add_u64 v[50:51], v[50:51], 0, s[18:19]
	global_store_dword v[50:51], v52, off
.LBB0_503:
	s_or_b64 exec, exec, s[0:1]
	v_add_u32_e32 v50, 0x90, v154
	v_ashrrev_i32_e32 v51, 31, v50
	v_lshlrev_b64 v[52:53], 11, v[50:51]
	v_lshl_add_u64 v[52:53], s[78:79], 0, v[52:53]
	v_lshl_add_u64 v[52:53], s[62:63], 1, v[52:53]
	v_lshl_add_u64 v[52:53], v[52:53], 0, s[70:71]
	v_lshl_add_u64 v[56:57], v[52:53], 0, v[0:1]
	v_cvt_pk_bf16_f32 v52, v46, v47
	v_mul_f32_e32 v47, v47, v47
	v_fmac_f32_e32 v47, v46, v46
	v_mul_f32_e32 v46, v39, v39
	v_fmac_f32_e32 v46, v38, v38
	v_fmac_f32_e32 v47, v48, v48
	v_fmac_f32_e32 v46, v40, v40
	v_fmac_f32_e32 v47, v49, v49
	v_fmac_f32_e32 v46, v41, v41
	v_fmac_f32_e32 v47, v42, v42
	v_fmac_f32_e32 v46, v34, v34
	v_fmac_f32_e32 v47, v43, v43
	v_fmac_f32_e32 v46, v35, v35
	v_fmac_f32_e32 v47, v44, v44
	v_fmac_f32_e32 v46, v36, v36
	v_fmac_f32_e32 v47, v45, v45
	v_fmac_f32_e32 v46, v37, v37
	v_add_f32_e32 v46, v47, v46
	ds_bpermute_b32 v47, v126, v46
	v_cvt_pk_bf16_f32 v53, v48, v49
	v_cvt_pk_bf16_f32 v54, v42, v43
	s_waitcnt lgkmcnt(0)
	v_cvt_pk_bf16_f32 v55, v44, v45
	global_store_dwordx4 v[56:57], v[52:55], off
	v_cvt_pk_bf16_f32 v42, v38, v39
	v_add_f32_e32 v38, v46, v47
	v_mov_b32_e32 v39, v38
	s_nop 1
	v_permlane32_swap_b32_e32 v39, v38
	v_cvt_pk_bf16_f32 v43, v40, v41
	v_cvt_pk_bf16_f32 v44, v34, v35
	v_cvt_pk_bf16_f32 v45, v36, v37
	global_store_dwordx4 v[56:57], v[42:45], off offset:256
	s_and_saveexec_b64 s[0:1], s[40:41]
	s_cbranch_execz .LBB0_505
	v_lshlrev_b64 v[34:35], 6, v[50:51]
	v_lshl_add_u64 v[34:35], s[66:67], 0, v[34:35]
	v_lshl_add_u64 v[34:35], s[60:61], 2, v[34:35]
	s_lshl_b32 s18, s21, 2
	s_mov_b32 s19, s71
	s_waitcnt lgkmcnt(0)
	v_add_f32_e32 v36, v38, v39
	v_lshl_add_u64 v[34:35], v[34:35], 0, s[18:19]
	global_store_dword v[34:35], v36, off

.LBB0_962:
	v_add_u32_e32 v34, s3, v91
	v_ashrrev_i32_e32 v35, 31, v34
	v_lshlrev_b64 v[36:37], 12, v[34:35]
	v_lshl_add_u64 v[36:37], v[96:97], 0, v[36:37]
	global_load_dwordx4 v[78:81], v[36:37], off
	global_load_dwordx4 v[74:77], v[36:37], off offset:16
	global_load_dwordx4 v[70:73], v[36:37], off offset:2048
	global_load_dwordx4 v[66:69], v[36:37], off offset:2064
	v_add_co_u32_e32 v138, vcc, 0x1000, v36
	s_nop 1
	v_addc_co_u32_e32 v139, vcc, 0, v37, vcc
	v_add_co_u32_e32 v140, vcc, 0x3000, v36
	s_nop 1
	v_addc_co_u32_e32 v141, vcc, 0, v37, vcc
	global_load_dwordx4 v[126:129], v[138:139], off
	global_load_dwordx4 v[130:133], v[138:139], off offset:16
	global_load_dwordx4 v[86:89], v[138:139], off offset:2048
	global_load_dwordx4 v[82:85], v[138:139], off offset:2064
	global_load_dwordx4 v[208:211], v[140:141], off offset:-4096
	global_load_dwordx4 v[212:215], v[140:141], off offset:-4080
	global_load_dwordx4 v[216:219], v[140:141], off offset:-2048
	global_load_dwordx4 v[220:223], v[140:141], off offset:-2032
	global_load_dwordx4 v[224:227], v[140:141], off
	global_load_dwordx4 v[228:231], v[140:141], off offset:16
	global_load_dwordx4 v[232:235], v[140:141], off offset:2048
	global_load_dwordx4 v[236:239], v[140:141], off offset:2064
	v_and_b32_e32 v0, 64, v199
	v_xor_b32_e32 v36, 32, v199
	v_add_u32_e32 v55, 64, v0
	v_xor_b32_e32 v37, 16, v199
	v_cmp_lt_i32_e32 vcc, v36, v55
	v_xor_b32_e32 v38, 8, v199
	v_xor_b32_e32 v52, 4, v199
	v_cndmask_b32_e32 v0, v199, v36, vcc
	v_cmp_lt_i32_e32 vcc, v37, v55
	v_lshlrev_b32_e32 v0, 2, v0
	v_xor_b32_e32 v53, 2, v199
	v_cndmask_b32_e32 v56, v199, v37, vcc
	v_cmp_lt_i32_e32 vcc, v38, v55
	v_lshlrev_b32_e32 v113, 2, v56
	v_add_u32_e32 v104, 1, v34
	v_cndmask_b32_e32 v57, v199, v38, vcc
	v_lshlrev_b32_e32 v114, 2, v57
	v_cmp_lt_i32_e32 vcc, v52, v55
	v_add_u32_e32 v102, 2, v34
	v_ashrrev_i32_e32 v105, 31, v104
	v_ashrrev_i32_e32 v103, 31, v102
	v_add_u32_e32 v100, 3, v34
	v_lshlrev_b64 v[34:35], 11, v[34:35]
	v_lshl_add_u64 v[134:135], v[98:99], 0, v[34:35]
	v_xor_b32_e32 v54, 1, v199
	s_mov_b32 s12, 0x800000
	v_ashrrev_i32_e32 v101, 31, v100
	s_waitcnt vmcnt(15)
	v_mov_b32_e32 v38, v79
	s_waitcnt vmcnt(14)
	v_mov_b32_e32 v39, v75
	v_mov_b32_e32 v36, v78
	v_mov_b32_e32 v37, v74
	s_waitcnt vmcnt(13)
	v_mov_b32_e32 v46, v71
	s_waitcnt vmcnt(12)
	v_mov_b32_e32 v47, v67
	v_pk_mul_f32 v[38:39], v[38:39], v[38:39]
	v_mov_b32_e32 v40, v80
	v_mov_b32_e32 v41, v76
	v_mov_b32_e32 v44, v70
	v_mov_b32_e32 v45, v66
	v_pk_mul_f32 v[46:47], v[46:47], v[46:47]
	v_pk_fma_f32 v[36:37], v[36:37], v[36:37], v[38:39]
	v_mov_b32_e32 v42, v81
	v_mov_b32_e32 v43, v77
	v_mov_b32_e32 v48, v72
	v_mov_b32_e32 v49, v68
	v_pk_fma_f32 v[38:39], v[44:45], v[44:45], v[46:47]
	v_pk_fma_f32 v[36:37], v[40:41], v[40:41], v[36:37]
	v_mov_b32_e32 v50, v73
	v_mov_b32_e32 v51, v69
	v_pk_fma_f32 v[38:39], v[48:49], v[48:49], v[38:39]
	v_pk_fma_f32 v[36:37], v[42:43], v[42:43], v[36:37]
	v_pk_fma_f32 v[38:39], v[50:51], v[50:51], v[38:39]
	v_add_f32_e32 v36, v36, v37
	v_add_f32_e32 v36, v36, v38
	v_add_f32_e32 v36, v36, v39
	v_mov_b32_e32 v37, v36
	s_nop 1
	v_permlane32_swap_b32_e32 v37, v36
	v_cndmask_b32_e32 v42, v199, v52, vcc
	v_cmp_lt_i32_e32 vcc, v53, v55
	v_lshlrev_b32_e32 v116, 2, v42
	v_lshlrev_b64 v[38:39], 12, v[102:103]
	s_waitcnt lgkmcnt(0)
	v_add_f32_e32 v40, v36, v37
	ds_bpermute_b32 v41, v113, v40
	v_cndmask_b32_e32 v43, v199, v53, vcc
	v_lshlrev_b32_e32 v115, 2, v43
	v_lshlrev_b64 v[36:37], 12, v[104:105]
	v_lshl_add_u64 v[34:35], v[96:97], 0, v[36:37]
	s_waitcnt lgkmcnt(0)
	v_add_f32_e32 v45, v40, v41
	s_nop 1
	v_mov_b32_dpp v46, v45 row_ror:8 row_mask:0xf bank_mask:0xf bound_ctrl:0
	v_lshl_add_u64 v[36:37], v[96:97], 0, v[38:39]
	v_cmp_lt_i32_e32 vcc, v54, v55
	v_cndmask_b32_e32 v44, v199, v54, vcc
	s_waitcnt lgkmcnt(0)
	v_add_f32_e32 v42, v45, v46
	s_nop 1
	v_mov_b32_dpp v43, v42 row_half_mirror row_mask:0xf bank_mask:0xf bound_ctrl:0
	v_lshlrev_b32_e32 v117, 2, v44
	v_lshlrev_b64 v[40:41], 12, v[100:101]
	v_lshl_add_u64 v[136:137], v[96:97], 0, v[40:41]
	s_waitcnt vmcnt(7)
	v_mov_b64_e32 v[62:63], v[208:209]
	v_mov_b64_e32 v[64:65], v[210:211]
	s_waitcnt vmcnt(6)
	v_mov_b64_e32 v[58:59], v[212:213]
	v_mov_b64_e32 v[60:61], v[214:215]
	s_waitcnt vmcnt(5)
	v_mov_b64_e32 v[54:55], v[216:217]
	v_mov_b64_e32 v[56:57], v[218:219]
	s_waitcnt vmcnt(4)
	v_mov_b64_e32 v[50:51], v[220:221]
	v_mov_b64_e32 v[52:53], v[222:223]
	s_waitcnt lgkmcnt(0)
	v_add_f32_e32 v38, v42, v43
	s_nop 1
	v_mov_b32_dpp v39, v38 quad_perm:[2,3,0,1] row_mask:0xf bank_mask:0xf bound_ctrl:0
	s_waitcnt lgkmcnt(0)
	v_add_f32_e32 v34, v38, v39
	s_nop 1
	v_mov_b32_dpp v35, v34 quad_perm:[1,0,3,2] row_mask:0xf bank_mask:0xf bound_ctrl:0
	s_waitcnt lgkmcnt(0)
	v_add_f32_e32 v34, v34, v35
	v_fmamk_f32 v34, v34, 0x3a800000, v198
	v_mul_f32_e32 v35, 0x4b800000, v34
	v_cmp_gt_f32_e32 vcc, s12, v34
	s_nop 1
	v_cndmask_b32_e32 v34, v34, v35, vcc
	v_rsq_f32_e32 v138, v34
	s_waitcnt vmcnt(3)
	v_mov_b64_e32 v[46:47], v[224:225]
	v_mov_b64_e32 v[48:49], v[226:227]
	s_waitcnt vmcnt(2)
	v_mov_b64_e32 v[42:43], v[228:229]
	v_mov_b64_e32 v[44:45], v[230:231]
	s_waitcnt vmcnt(1)
	v_mov_b64_e32 v[38:39], v[232:233]
	v_mov_b64_e32 v[40:41], v[234:235]
	s_waitcnt vmcnt(0)
	v_mov_b64_e32 v[34:35], v[236:237]
	v_mov_b64_e32 v[36:37], v[238:239]
	v_mul_f32_e32 v136, 0x45800000, v138
	v_cndmask_b32_e32 v136, v138, v136, vcc
	v_pk_mul_f32 v[74:75], v[74:75], v[136:137] op_sel_hi:[1,0]
	v_pk_mul_f32 v[76:77], v[76:77], v[136:137] op_sel_hi:[1,0]
	v_pk_mul_f32 v[78:79], v[78:79], v[136:137] op_sel_hi:[1,0]
	v_pk_mul_f32 v[80:81], v[80:81], v[136:137] op_sel_hi:[1,0]
	v_pk_mul_f32 v[120:121], v[166:167], v[76:77]
	v_pk_mul_f32 v[76:77], v[164:165], v[74:75]
	v_pk_mul_f32 v[80:81], v[162:163], v[80:81]
	v_pk_mul_f32 v[78:79], v[160:161], v[78:79]
	v_pk_mul_f32 v[70:71], v[70:71], v[136:137] op_sel_hi:[1,0]
	v_cvt_pk_bf16_f32 v74, v78, v79
	v_cvt_pk_bf16_f32 v75, v80, v81
	v_cvt_pk_bf16_f32 v76, v76, v77
	v_cvt_pk_bf16_f32 v77, v120, v121
	global_store_dwordx4 v[134:135], v[74:77], off
	s_nop 0
	v_pk_mul_f32 v[66:67], v[66:67], v[136:137] op_sel_hi:[1,0]
	v_pk_mul_f32 v[68:69], v[68:69], v[136:137] op_sel_hi:[1,0]
	v_pk_mul_f32 v[72:73], v[72:73], v[136:137] op_sel_hi:[1,0]
	v_mov_b32_e32 v118, v128
	v_mov_b32_e32 v119, v132
	v_mov_b32_e32 v120, v88
	v_mov_b32_e32 v121, v84
	v_mov_b32_e32 v122, v129
	v_mov_b32_e32 v123, v133
	v_mov_b32_e32 v124, v89
	v_mov_b32_e32 v125, v85
	v_pk_mul_f32 v[70:71], v[168:169], v[70:71]
	v_pk_mul_f32 v[74:75], v[174:175], v[68:69]
	v_pk_mul_f32 v[68:69], v[172:173], v[66:67]
	v_pk_mul_f32 v[72:73], v[170:171], v[72:73]
	v_cvt_pk_bf16_f32 v66, v70, v71
	v_mov_b32_e32 v76, v127
	v_cvt_pk_bf16_f32 v67, v72, v73
	v_cvt_pk_bf16_f32 v68, v68, v69
	v_cvt_pk_bf16_f32 v69, v74, v75
	global_store_dwordx4 v[134:135], v[66:69], off offset:1024
	s_nop 0
	v_mov_b32_e32 v77, v131
	v_mov_b32_e32 v74, v126
	v_mov_b32_e32 v75, v130
	v_mov_b32_e32 v80, v87
	v_mov_b32_e32 v81, v83
	v_pk_mul_f32 v[76:77], v[76:77], v[76:77]
	v_mov_b32_e32 v78, v86
	v_mov_b32_e32 v79, v82
	v_pk_mul_f32 v[80:81], v[80:81], v[80:81]
	v_pk_fma_f32 v[74:75], v[74:75], v[74:75], v[76:77]
	v_pk_fma_f32 v[76:77], v[78:79], v[78:79], v[80:81]
	v_pk_fma_f32 v[74:75], v[118:119], v[118:119], v[74:75]
	v_pk_fma_f32 v[76:77], v[120:121], v[120:121], v[76:77]
	v_pk_fma_f32 v[74:75], v[122:123], v[122:123], v[74:75]
	v_pk_fma_f32 v[76:77], v[124:125], v[124:125], v[76:77]
	v_add_f32_e32 v74, v74, v75
	v_add_f32_e32 v74, v74, v76
	v_add_f32_e32 v74, v74, v77
	v_mov_b32_e32 v75, v74
	s_nop 1
	v_permlane32_swap_b32_e32 v75, v74
	s_waitcnt lgkmcnt(0)
	v_add_f32_e32 v74, v74, v75
	ds_bpermute_b32 v75, v113, v74
	s_waitcnt lgkmcnt(0)
	v_add_f32_e32 v74, v74, v75
	s_nop 1
	v_mov_b32_dpp v75, v74 row_ror:8 row_mask:0xf bank_mask:0xf bound_ctrl:0
	s_waitcnt lgkmcnt(0)
	v_add_f32_e32 v74, v74, v75
	s_nop 1
	v_mov_b32_dpp v75, v74 row_half_mirror row_mask:0xf bank_mask:0xf bound_ctrl:0
	s_waitcnt lgkmcnt(0)
	v_add_f32_e32 v74, v74, v75
	s_nop 1
	v_mov_b32_dpp v75, v74 quad_perm:[2,3,0,1] row_mask:0xf bank_mask:0xf bound_ctrl:0
	s_waitcnt lgkmcnt(0)
	v_add_f32_e32 v74, v74, v75
	s_nop 1
	v_mov_b32_dpp v75, v74 quad_perm:[1,0,3,2] row_mask:0xf bank_mask:0xf bound_ctrl:0
	s_waitcnt lgkmcnt(0)
	v_add_f32_e32 v74, v74, v75
	v_fmamk_f32 v74, v74, 0x3a800000, v198
	v_mul_f32_e32 v75, 0x4b800000, v74
	v_cmp_gt_f32_e32 vcc, s12, v74
	s_nop 1
	v_cndmask_b32_e32 v74, v74, v75, vcc
	v_rsq_f32_e32 v76, v74
	v_lshlrev_b64 v[74:75], 11, v[104:105]
	v_lshl_add_u64 v[74:75], v[98:99], 0, v[74:75]
	v_mul_f32_e32 v77, 0x45800000, v76
	v_cndmask_b32_e32 v76, v76, v77, vcc
	v_pk_mul_f32 v[78:79], v[126:127], v[76:77] op_sel_hi:[1,0]
	v_pk_mul_f32 v[80:81], v[128:129], v[76:77] op_sel_hi:[1,0]
	v_pk_mul_f32 v[104:105], v[130:131], v[76:77] op_sel_hi:[1,0]
	v_pk_mul_f32 v[118:119], v[132:133], v[76:77] op_sel_hi:[1,0]
	v_pk_mul_f32 v[82:83], v[82:83], v[76:77] op_sel_hi:[1,0]
	v_pk_mul_f32 v[68:69], v[162:163], v[80:81]
	v_pk_mul_f32 v[66:67], v[160:161], v[78:79]
	v_pk_mul_f32 v[72:73], v[166:167], v[118:119]
	v_pk_mul_f32 v[70:71], v[164:165], v[104:105]
	v_cvt_pk_bf16_f32 v66, v66, v67
	v_cvt_pk_bf16_f32 v67, v68, v69
	v_pk_mul_f32 v[78:79], v[86:87], v[76:77] op_sel_hi:[1,0]
	v_cvt_pk_bf16_f32 v68, v70, v71
	v_cvt_pk_bf16_f32 v69, v72, v73
	global_store_dwordx4 v[74:75], v[66:69], off
	s_nop 0
	v_pk_mul_f32 v[80:81], v[88:89], v[76:77] op_sel_hi:[1,0]
	v_pk_mul_f32 v[76:77], v[84:85], v[76:77] op_sel_hi:[1,0]
	v_mov_b32_e32 v84, v65
	v_mov_b32_e32 v85, v61
	v_mov_b32_e32 v86, v56
	v_mov_b32_e32 v87, v52
	v_mov_b32_e32 v88, v57
	v_mov_b32_e32 v89, v53
	v_pk_mul_f32 v[68:69], v[170:171], v[80:81]
	v_pk_mul_f32 v[66:67], v[168:169], v[78:79]
	v_pk_mul_f32 v[72:73], v[174:175], v[76:77]
	v_pk_mul_f32 v[70:71], v[172:173], v[82:83]
	v_cvt_pk_bf16_f32 v66, v66, v67
	v_cvt_pk_bf16_f32 v67, v68, v69
	v_mov_b32_e32 v76, v63
	v_cvt_pk_bf16_f32 v68, v70, v71
	v_cvt_pk_bf16_f32 v69, v72, v73
	global_store_dwordx4 v[74:75], v[66:69], off offset:1024
	s_nop 0
	v_mov_b32_e32 v77, v59
	v_mov_b32_e32 v74, v62
	v_mov_b32_e32 v75, v58
	v_mov_b32_e32 v82, v55
	v_mov_b32_e32 v83, v51
	v_pk_mul_f32 v[76:77], v[76:77], v[76:77]
	v_mov_b32_e32 v78, v64
	v_mov_b32_e32 v79, v60
	v_mov_b32_e32 v80, v54
	v_mov_b32_e32 v81, v50
	v_pk_mul_f32 v[82:83], v[82:83], v[82:83]
	v_pk_fma_f32 v[74:75], v[74:75], v[74:75], v[76:77]
	v_pk_fma_f32 v[76:77], v[80:81], v[80:81], v[82:83]
	v_pk_fma_f32 v[74:75], v[78:79], v[78:79], v[74:75]
	v_pk_fma_f32 v[76:77], v[86:87], v[86:87], v[76:77]
	v_pk_fma_f32 v[74:75], v[84:85], v[84:85], v[74:75]
	v_pk_fma_f32 v[76:77], v[88:89], v[88:89], v[76:77]
	v_add_f32_e32 v74, v74, v75
	v_add_f32_e32 v74, v74, v76
	v_add_f32_e32 v74, v74, v77
	v_mov_b32_e32 v75, v74
	s_nop 1
	v_permlane32_swap_b32_e32 v75, v74
	s_waitcnt lgkmcnt(0)
	v_add_f32_e32 v74, v74, v75
	ds_bpermute_b32 v75, v113, v74
	s_waitcnt lgkmcnt(0)
	v_add_f32_e32 v74, v74, v75
	s_nop 1
	v_mov_b32_dpp v75, v74 row_ror:8 row_mask:0xf bank_mask:0xf bound_ctrl:0
	s_waitcnt lgkmcnt(0)
	v_add_f32_e32 v74, v74, v75
	s_nop 1
	v_mov_b32_dpp v75, v74 row_half_mirror row_mask:0xf bank_mask:0xf bound_ctrl:0
	s_waitcnt lgkmcnt(0)
	v_add_f32_e32 v74, v74, v75
	s_nop 1
	v_mov_b32_dpp v75, v74 quad_perm:[2,3,0,1] row_mask:0xf bank_mask:0xf bound_ctrl:0
	s_waitcnt lgkmcnt(0)
	v_add_f32_e32 v74, v74, v75
	s_nop 1
	v_mov_b32_dpp v75, v74 quad_perm:[1,0,3,2] row_mask:0xf bank_mask:0xf bound_ctrl:0
	s_waitcnt lgkmcnt(0)
	v_add_f32_e32 v74, v74, v75
	v_fmamk_f32 v74, v74, 0x3a800000, v198
	v_mul_f32_e32 v75, 0x4b800000, v74
	v_cmp_gt_f32_e32 vcc, s12, v74
	s_nop 1
	v_cndmask_b32_e32 v74, v74, v75, vcc
	v_rsq_f32_e32 v76, v74
	v_lshlrev_b64 v[74:75], 11, v[102:103]
	v_lshl_add_u64 v[74:75], v[98:99], 0, v[74:75]
	v_mul_f32_e32 v77, 0x45800000, v76
	v_cndmask_b32_e32 v76, v76, v77, vcc
	v_pk_mul_f32 v[62:63], v[62:63], v[76:77] op_sel_hi:[1,0]
	v_pk_mul_f32 v[58:59], v[58:59], v[76:77] op_sel_hi:[1,0]
	v_pk_mul_f32 v[60:61], v[60:61], v[76:77] op_sel_hi:[1,0]
	v_pk_mul_f32 v[64:65], v[64:65], v[76:77] op_sel_hi:[1,0]
	v_pk_mul_f32 v[54:55], v[54:55], v[76:77] op_sel_hi:[1,0]
	v_pk_mul_f32 v[50:51], v[50:51], v[76:77] op_sel_hi:[1,0]
	v_pk_mul_f32 v[52:53], v[52:53], v[76:77] op_sel_hi:[1,0]
	v_pk_mul_f32 v[56:57], v[56:57], v[76:77] op_sel_hi:[1,0]
	v_pk_mul_f32 v[62:63], v[160:161], v[62:63]
	v_pk_mul_f32 v[66:67], v[166:167], v[60:61]
	v_pk_mul_f32 v[60:61], v[164:165], v[58:59]
	v_pk_mul_f32 v[64:65], v[162:163], v[64:65]
	v_cvt_pk_bf16_f32 v58, v62, v63
	v_mov_b32_e32 v68, v39
	v_cvt_pk_bf16_f32 v59, v64, v65
	v_cvt_pk_bf16_f32 v60, v60, v61
	v_cvt_pk_bf16_f32 v61, v66, v67
	global_store_dwordx4 v[74:75], v[58:61], off
	s_nop 0
	v_mov_b32_e32 v69, v35
	v_mov_b32_e32 v66, v38
	v_mov_b32_e32 v67, v34
	v_pk_mul_f32 v[68:69], v[68:69], v[68:69]
	v_mov_b32_e32 v70, v40
	v_mov_b32_e32 v71, v36
	v_mov_b32_e32 v72, v41
	v_mov_b32_e32 v73, v37
	v_pk_mul_f32 v[54:55], v[168:169], v[54:55]
	v_pk_mul_f32 v[58:59], v[174:175], v[52:53]
	v_pk_mul_f32 v[52:53], v[172:173], v[50:51]
	v_pk_mul_f32 v[56:57], v[170:171], v[56:57]
	v_cvt_pk_bf16_f32 v50, v54, v55
	v_mov_b32_e32 v60, v47
	v_cvt_pk_bf16_f32 v51, v56, v57
	v_cvt_pk_bf16_f32 v52, v52, v53
	v_cvt_pk_bf16_f32 v53, v58, v59
	global_store_dwordx4 v[74:75], v[50:53], off offset:1024
	s_nop 0
	v_mov_b32_e32 v61, v43
	v_mov_b32_e32 v58, v46
	v_mov_b32_e32 v59, v42
	v_pk_mul_f32 v[60:61], v[60:61], v[60:61]
	v_mov_b32_e32 v62, v48
	v_mov_b32_e32 v63, v44
	v_pk_fma_f32 v[58:59], v[58:59], v[58:59], v[60:61]
	v_mov_b32_e32 v64, v49
	v_mov_b32_e32 v65, v45
	v_pk_fma_f32 v[60:61], v[66:67], v[66:67], v[68:69]
	v_pk_fma_f32 v[58:59], v[62:63], v[62:63], v[58:59]
	v_pk_fma_f32 v[60:61], v[70:71], v[70:71], v[60:61]
	v_pk_fma_f32 v[58:59], v[64:65], v[64:65], v[58:59]
	v_pk_fma_f32 v[60:61], v[72:73], v[72:73], v[60:61]
	v_add_f32_e32 v58, v58, v59
	v_add_f32_e32 v58, v58, v60
	v_add_f32_e32 v58, v58, v61
	v_mov_b32_e32 v0, v58
	s_nop 1
	v_permlane32_swap_b32_e32 v0, v58
	s_waitcnt lgkmcnt(0)
	v_add_f32_e32 v0, v58, v0
	ds_bpermute_b32 v58, v113, v0
	s_waitcnt lgkmcnt(0)
	v_add_f32_e32 v0, v0, v58
	s_nop 1
	v_mov_b32_dpp v58, v0 row_ror:8 row_mask:0xf bank_mask:0xf bound_ctrl:0
	s_waitcnt lgkmcnt(0)
	v_add_f32_e32 v0, v0, v58
	s_nop 1
	v_mov_b32_dpp v58, v0 row_half_mirror row_mask:0xf bank_mask:0xf bound_ctrl:0
	s_waitcnt lgkmcnt(0)
	v_add_f32_e32 v0, v0, v58
	s_nop 1
	v_mov_b32_dpp v58, v0 quad_perm:[2,3,0,1] row_mask:0xf bank_mask:0xf bound_ctrl:0
	s_waitcnt lgkmcnt(0)
	v_add_f32_e32 v0, v0, v58
	s_nop 1
	v_mov_b32_dpp v58, v0 quad_perm:[1,0,3,2] row_mask:0xf bank_mask:0xf bound_ctrl:0
	s_waitcnt lgkmcnt(0)
	v_add_f32_e32 v0, v0, v58
	v_fmamk_f32 v0, v0, 0x3a800000, v198
	v_mul_f32_e32 v58, 0x4b800000, v0
	v_cmp_gt_f32_e32 vcc, s12, v0
	s_nop 1
	v_cndmask_b32_e32 v0, v0, v58, vcc
	v_rsq_f32_e32 v0, v0
	v_lshlrev_b64 v[58:59], 11, v[100:101]
	v_lshl_add_u64 v[58:59], v[98:99], 0, v[58:59]
	v_mul_f32_e32 v60, 0x45800000, v0
	v_cndmask_b32_e32 v0, v0, v60, vcc
	v_pk_mul_f32 v[46:47], v[46:47], v[0:1] op_sel_hi:[1,0]
	v_pk_mul_f32 v[42:43], v[42:43], v[0:1] op_sel_hi:[1,0]
	v_pk_mul_f32 v[44:45], v[44:45], v[0:1] op_sel_hi:[1,0]
	v_pk_mul_f32 v[48:49], v[48:49], v[0:1] op_sel_hi:[1,0]
	v_pk_mul_f32 v[38:39], v[38:39], v[0:1] op_sel_hi:[1,0]
	v_pk_mul_f32 v[34:35], v[34:35], v[0:1] op_sel_hi:[1,0]
	v_pk_mul_f32 v[36:37], v[36:37], v[0:1] op_sel_hi:[1,0]
	v_pk_mul_f32 v[40:41], v[40:41], v[0:1] op_sel_hi:[1,0]
	v_pk_mul_f32 v[46:47], v[160:161], v[46:47]
	v_pk_mul_f32 v[50:51], v[166:167], v[44:45]
	v_pk_mul_f32 v[44:45], v[164:165], v[42:43]
	v_pk_mul_f32 v[48:49], v[162:163], v[48:49]
	v_cvt_pk_bf16_f32 v42, v46, v47
	s_nop 0
	v_cvt_pk_bf16_f32 v43, v48, v49
	v_cvt_pk_bf16_f32 v44, v44, v45
	v_cvt_pk_bf16_f32 v45, v50, v51
	global_store_dwordx4 v[58:59], v[42:45], off
	s_nop 0
	v_pk_mul_f32 v[38:39], v[168:169], v[38:39]
	v_pk_mul_f32 v[42:43], v[174:175], v[36:37]
	v_pk_mul_f32 v[36:37], v[172:173], v[34:35]
	v_pk_mul_f32 v[40:41], v[170:171], v[40:41]
	v_cvt_pk_bf16_f32 v34, v38, v39
	s_nop 0
	v_cvt_pk_bf16_f32 v35, v40, v41
	v_cvt_pk_bf16_f32 v36, v36, v37
	v_cvt_pk_bf16_f32 v37, v42, v43
	global_store_dwordx4 v[58:59], v[34:37], off offset:1024
	s_or_b64 exec, exec, s[14:15]
	s_andn2_b64 vcc, exec, s[6:7]
	s_cbranch_vccnz .LBB0_955
	s_branch .LBB0_1000

.LBB0_1040:
	v_add_u32_e32 v14, 0x8000, v93
	v_cmp_gt_i32_e32 vcc, s94, v14
	v_mov_b32_e32 v16, s11
	v_mov_b32_e32 v17, s9
	v_mov_b32_e32 v18, s10
	v_mov_b32_e32 v19, s8
	v_cndmask_b32_e32 v15, 0, v3, vcc
	v_cndmask_b32_e32 v14, v93, v2, vcc
	v_cndmask_b32_e32 v17, v16, v17, vcc
	v_cndmask_b32_e32 v16, v18, v19, vcc
	v_lshlrev_b64 v[14:15], 12, v[14:15]
	v_lshl_add_u64 v[14:15], v[16:17], 0, v[14:15]
	v_lshl_add_u64 v[26:27], v[14:15], 0, v[0:1]
	global_load_dwordx4 v[14:17], v[26:27], off
	global_load_dwordx4 v[18:21], v[26:27], off offset:16
	global_load_dwordx4 v[22:25], v[26:27], off offset:2048
	s_nop 0
	global_load_dwordx4 v[26:29], v[26:27], off offset:2064
	s_nop 0
	global_load_dwordx4 v[30:33], v[4:5], off
	global_load_dwordx4 v[34:37], v[4:5], off offset:16
	v_add_u32_e32 v93, s42, v93
	s_mov_b32 s2, 0x80ff
	v_lshl_add_u64 v[2:3], v[2:3], 0, s[42:43]
	s_waitcnt vmcnt(5)
	v_mov_b32_e32 v40, v15
	s_waitcnt vmcnt(4)
	v_mov_b32_e32 v41, v19
	v_mov_b32_e32 v38, v14
	v_mov_b32_e32 v39, v18
	s_waitcnt vmcnt(3)
	v_mov_b32_e32 v48, v23
	s_waitcnt vmcnt(2)
	v_mov_b32_e32 v49, v27
	v_pk_mul_f32 v[40:41], v[40:41], v[40:41]
	v_mov_b32_e32 v42, v16
	v_mov_b32_e32 v43, v20
	v_mov_b32_e32 v46, v22
	v_mov_b32_e32 v47, v26
	v_pk_mul_f32 v[48:49], v[48:49], v[48:49]
	v_pk_fma_f32 v[38:39], v[38:39], v[38:39], v[40:41]
	v_mov_b32_e32 v44, v17
	v_mov_b32_e32 v45, v21
	v_mov_b32_e32 v50, v24
	v_mov_b32_e32 v51, v28
	v_pk_fma_f32 v[40:41], v[46:47], v[46:47], v[48:49]
	v_pk_fma_f32 v[38:39], v[42:43], v[42:43], v[38:39]
	v_mov_b32_e32 v52, v25
	v_mov_b32_e32 v53, v29
	v_pk_fma_f32 v[40:41], v[50:51], v[50:51], v[40:41]
	v_pk_fma_f32 v[38:39], v[44:45], v[44:45], v[38:39]
	v_pk_fma_f32 v[40:41], v[52:53], v[52:53], v[40:41]
	v_add_f32_e32 v38, v38, v39
	v_add_f32_e32 v38, v38, v40
	v_add_f32_e32 v38, v38, v41
	v_mov_b32_e32 v39, v38
	s_nop 1
	v_permlane32_swap_b32_e32 v39, v38
	s_waitcnt lgkmcnt(0)
	v_add_f32_e32 v38, v38, v39
	ds_bpermute_b32 v39, v10, v38
	s_waitcnt lgkmcnt(0)
	v_add_f32_e32 v38, v38, v39
	s_nop 1
	v_mov_b32_dpp v39, v38 row_ror:8 row_mask:0xf bank_mask:0xf bound_ctrl:0
	s_waitcnt lgkmcnt(0)
	v_add_f32_e32 v38, v38, v39
	s_nop 1
	v_mov_b32_dpp v39, v38 row_half_mirror row_mask:0xf bank_mask:0xf bound_ctrl:0
	s_waitcnt lgkmcnt(0)
	v_add_f32_e32 v38, v38, v39
	s_nop 1
	v_mov_b32_dpp v39, v38 quad_perm:[2,3,0,1] row_mask:0xf bank_mask:0xf bound_ctrl:0
	s_waitcnt lgkmcnt(0)
	v_add_f32_e32 v38, v38, v39
	s_nop 1
	v_mov_b32_dpp v39, v38 quad_perm:[1,0,3,2] row_mask:0xf bank_mask:0xf bound_ctrl:0
	s_waitcnt lgkmcnt(0)
	v_add_f32_e32 v38, v38, v39
	v_fmamk_f32 v38, v38, 0x3a800000, v198
	v_mul_f32_e32 v39, 0x4b800000, v38
	v_cmp_gt_f32_e32 vcc, s6, v38
	s_nop 1
	v_cndmask_b32_e32 v38, v38, v39, vcc
	v_rsq_f32_e32 v38, v38
	s_nop 0
	v_mul_f32_e32 v39, 0x45800000, v38
	v_cndmask_b32_e32 v38, v38, v39, vcc
	v_pk_mul_f32 v[14:15], v[14:15], v[38:39] op_sel_hi:[1,0]
	v_pk_mul_f32 v[16:17], v[16:17], v[38:39] op_sel_hi:[1,0]
	v_pk_mul_f32 v[18:19], v[18:19], v[38:39] op_sel_hi:[1,0]
	v_pk_mul_f32 v[20:21], v[20:21], v[38:39] op_sel_hi:[1,0]
	s_waitcnt vmcnt(1)
	v_pk_mul_f32 v[16:17], v[32:33], v[16:17]
	v_pk_mul_f32 v[14:15], v[30:31], v[14:15]
	s_waitcnt vmcnt(0)
	v_pk_mul_f32 v[20:21], v[36:37], v[20:21]
	v_pk_mul_f32 v[18:19], v[34:35], v[18:19]
	v_cvt_pk_bf16_f32 v14, v14, v15
	v_cvt_pk_bf16_f32 v15, v16, v17
	v_add_u32_e32 v30, 0x8000, v93
	v_cvt_pk_bf16_f32 v16, v18, v19
	v_cvt_pk_bf16_f32 v17, v20, v21
	global_store_dwordx4 v[6:7], v[14:17], off offset:-1024
	global_load_dwordx4 v[14:17], v[4:5], off offset:2048
	s_nop 0
	global_load_dwordx4 v[18:21], v[4:5], off offset:2064
	v_pk_mul_f32 v[22:23], v[22:23], v[38:39] op_sel_hi:[1,0]
	v_pk_mul_f32 v[24:25], v[24:25], v[38:39] op_sel_hi:[1,0]
	v_cmp_lt_i32_e32 vcc, s2, v30
	v_pk_mul_f32 v[26:27], v[26:27], v[38:39] op_sel_hi:[1,0]
	v_pk_mul_f32 v[28:29], v[28:29], v[38:39] op_sel_hi:[1,0]
	s_or_b64 s[4:5], vcc, s[4:5]
	s_waitcnt vmcnt(1)
	v_pk_mul_f32 v[16:17], v[16:17], v[24:25]
	v_pk_mul_f32 v[14:15], v[14:15], v[22:23]
	s_waitcnt vmcnt(0)
	v_pk_mul_f32 v[20:21], v[20:21], v[28:29]
	v_pk_mul_f32 v[18:19], v[18:19], v[26:27]
	v_cvt_pk_bf16_f32 v14, v14, v15
	v_cvt_pk_bf16_f32 v15, v16, v17
	s_nop 0
	v_cvt_pk_bf16_f32 v16, v18, v19
	v_cvt_pk_bf16_f32 v17, v20, v21
	global_store_dwordx4 v[6:7], v[14:17], off
	v_lshl_add_u64 v[6:7], v[6:7], 0, s[38:39]
	s_andn2_b64 exec, exec, s[4:5]
	s_cbranch_execnz .LBB0_1040
	s_branch .LBB0_4
